# side_kv: 64 weight-row loads per K half in flight instead of one serial round trip per row
# speedup vs baseline: 1.1302x; 1.0033x over previous
.LBB0_830:
	s_lshl_b32 s0, s3, 2
	s_and_b32 s5, s0, 0x1f00
	s_ashr_i32 s0, s2, 2
	s_lshr_b32 s4, s2, 2
	s_and_b32 s0, s0, 0xffffff80
	s_and_b32 s4, s4, 0x78
	s_ashr_i32 s1, s0, 31
	s_lshl_b32 s6, s4, 12
	v_readlane_b32 s7, v251, 30
	s_add_u32 s8, s7, s6
	v_readlane_b32 s6, v251, 31
	s_addc_u32 s9, s6, 0
	s_lshl_b64 s[6:7], s[0:1], 2
	s_add_u32 s6, s8, s6
	s_addc_u32 s7, s9, s7
	v_lshl_add_u64 v[4:5], s[6:7], 0, v[0:1]
	s_movk_i32 s1, 0x2000
	v_add_co_u32_e32 v6, vcc, s1, v4
	s_movk_i32 s1, 0x4000
	s_nop 0
	v_addc_co_u32_e32 v7, vcc, 0, v5, vcc
	global_load_dword v3, v0, s[6:7]
	global_load_dword v19, v[6:7], off offset:-4096
	global_load_dword v20, v[6:7], off
	v_add_co_u32_e32 v6, vcc, s1, v4
	s_movk_i32 s1, 0x5000
	s_nop 0
	v_addc_co_u32_e32 v7, vcc, 0, v5, vcc
	global_load_dword v21, v[6:7], off offset:-4096
	global_load_dword v22, v[6:7], off
	v_add_co_u32_e32 v6, vcc, s1, v4
	s_mul_hi_i32 s1, s0, 0xe0c0
	s_nop 0
	v_addc_co_u32_e32 v7, vcc, 0, v5, vcc
	global_load_dword v23, v[6:7], off
	v_add_co_u32_e32 v6, vcc, 0x6000, v4
	v_readlane_b32 s6, v254, 30
	s_nop 0
	v_addc_co_u32_e32 v7, vcc, 0, v5, vcc
	global_load_dword v24, v[6:7], off
	v_add_co_u32_e32 v6, vcc, 0x7000, v4
	v_readlane_b32 s7, v254, 31
	s_nop 0
	v_addc_co_u32_e32 v7, vcc, 0, v5, vcc
	global_load_dword v25, v[6:7], off
	v_lshl_or_b32 v6, v2, 2, s5
	s_mul_i32 s5, s0, 0xe0c0
	v_or_b32_e32 v6, s5, v6
	v_mov_b32_e32 v7, s1
	v_mov_b32_e32 v16, 0
	s_mov_b32 s0, 0
	v_lshl_add_u64 v[8:9], s[6:7], 0, v[6:7]
	v_mov_b32_e32 v17, v16
	v_mov_b32_e32 v14, v16
	v_mov_b32_e32 v15, v16
	v_mov_b32_e32 v12, v16
	v_mov_b32_e32 v13, v16
	v_mov_b32_e32 v10, v16
	v_mov_b32_e32 v11, v16
	s_mov_b32 s5, 0x2a000
	s_mov_b32 s14, 0x38000
	s_mov_b32 s15, 0x46000
	s_mov_b32 s16, 0x54000
	s_mov_b32 s17, 0x62000
	s_mov_b32 s18, 0xfff9e000
	s_mov_b32 s22, 0xfffac000
	s_mov_b32 s23, 0xfffba000
	s_mov_b32 s24, 0xfffc8000
	s_mov_b32 s25, 0xfffd6000
	s_mov_b32 s26, 0xfffe4000
	s_mov_b32 s27, 0xffff2000
	s_mov_b64 s[30:31], 0xe0c00
	s_mov_b32 s34, 0x1c000
	s_mov_b32 s35, 0xe000
	s_mov_b32 s16, 0x1000
	s_mov_b32 s17, 0
	v_mov_b32_e32 v34, v4
	v_mov_b32_e32 v35, v5
	global_load_dword v26, v[34:35], off offset:256
	v_lshl_add_u64 v[34:35], v[34:35], 0, s[16:17]
	global_load_dword v27, v[34:35], off offset:256
	v_lshl_add_u64 v[34:35], v[34:35], 0, s[16:17]
	global_load_dword v28, v[34:35], off offset:256
	v_lshl_add_u64 v[34:35], v[34:35], 0, s[16:17]
	global_load_dword v29, v[34:35], off offset:256
	v_lshl_add_u64 v[34:35], v[34:35], 0, s[16:17]
	global_load_dword v30, v[34:35], off offset:256
	v_lshl_add_u64 v[34:35], v[34:35], 0, s[16:17]
	global_load_dword v31, v[34:35], off offset:256
	v_lshl_add_u64 v[34:35], v[34:35], 0, s[16:17]
	global_load_dword v32, v[34:35], off offset:256
	v_lshl_add_u64 v[34:35], v[34:35], 0, s[16:17]
	global_load_dword v33, v[34:35], off offset:256
	s_mov_b32 s14, 0xfff8fa00
	s_mov_b32 s15, -1
	v_lshl_add_u64 v[8:9], v[8:9], 0, s[14:15]
	s_mov_b32 s14, 0xe0c0
	s_mov_b32 s15, 0
	global_load_dword v40, v[8:9], off
	v_lshl_add_u64 v[8:9], v[8:9], 0, s[14:15]
	global_load_dword v42, v[8:9], off
	v_lshl_add_u64 v[8:9], v[8:9], 0, s[14:15]
	global_load_dword v44, v[8:9], off
	v_lshl_add_u64 v[8:9], v[8:9], 0, s[14:15]
	global_load_dword v46, v[8:9], off
	v_lshl_add_u64 v[8:9], v[8:9], 0, s[14:15]
	global_load_dword v48, v[8:9], off
	v_lshl_add_u64 v[8:9], v[8:9], 0, s[14:15]
	global_load_dword v50, v[8:9], off
	v_lshl_add_u64 v[8:9], v[8:9], 0, s[14:15]
	global_load_dword v52, v[8:9], off
	v_lshl_add_u64 v[8:9], v[8:9], 0, s[14:15]
	global_load_dword v54, v[8:9], off
	v_lshl_add_u64 v[8:9], v[8:9], 0, s[14:15]
	global_load_dword v56, v[8:9], off
	v_lshl_add_u64 v[8:9], v[8:9], 0, s[14:15]
	global_load_dword v58, v[8:9], off
	v_lshl_add_u64 v[8:9], v[8:9], 0, s[14:15]
	global_load_dword v60, v[8:9], off
	v_lshl_add_u64 v[8:9], v[8:9], 0, s[14:15]
	global_load_dword v62, v[8:9], off
	v_lshl_add_u64 v[8:9], v[8:9], 0, s[14:15]
	global_load_dword v64, v[8:9], off
	v_lshl_add_u64 v[8:9], v[8:9], 0, s[14:15]
	global_load_dword v66, v[8:9], off
	v_lshl_add_u64 v[8:9], v[8:9], 0, s[14:15]
	global_load_dword v68, v[8:9], off
	v_lshl_add_u64 v[8:9], v[8:9], 0, s[14:15]
	global_load_dword v70, v[8:9], off
	v_lshl_add_u64 v[8:9], v[8:9], 0, s[14:15]
	global_load_dword v72, v[8:9], off
	v_lshl_add_u64 v[8:9], v[8:9], 0, s[14:15]
	global_load_dword v74, v[8:9], off
	v_lshl_add_u64 v[8:9], v[8:9], 0, s[14:15]
	global_load_dword v76, v[8:9], off
	v_lshl_add_u64 v[8:9], v[8:9], 0, s[14:15]
	global_load_dword v78, v[8:9], off
	v_lshl_add_u64 v[8:9], v[8:9], 0, s[14:15]
	global_load_dword v80, v[8:9], off
	v_lshl_add_u64 v[8:9], v[8:9], 0, s[14:15]
	global_load_dword v82, v[8:9], off
	v_lshl_add_u64 v[8:9], v[8:9], 0, s[14:15]
	global_load_dword v84, v[8:9], off
	v_lshl_add_u64 v[8:9], v[8:9], 0, s[14:15]
	global_load_dword v86, v[8:9], off
	v_lshl_add_u64 v[8:9], v[8:9], 0, s[14:15]
	global_load_dword v88, v[8:9], off
	v_lshl_add_u64 v[8:9], v[8:9], 0, s[14:15]
	global_load_dword v90, v[8:9], off
	v_lshl_add_u64 v[8:9], v[8:9], 0, s[14:15]
	global_load_dword v92, v[8:9], off
	v_lshl_add_u64 v[8:9], v[8:9], 0, s[14:15]
	global_load_dword v94, v[8:9], off
	v_lshl_add_u64 v[8:9], v[8:9], 0, s[14:15]
	global_load_dword v96, v[8:9], off
	v_lshl_add_u64 v[8:9], v[8:9], 0, s[14:15]
	global_load_dword v98, v[8:9], off
	v_lshl_add_u64 v[8:9], v[8:9], 0, s[14:15]
	global_load_dword v100, v[8:9], off
	v_lshl_add_u64 v[8:9], v[8:9], 0, s[14:15]
	global_load_dword v102, v[8:9], off
	v_lshl_add_u64 v[8:9], v[8:9], 0, s[14:15]
	global_load_dword v104, v[8:9], off
	v_lshl_add_u64 v[8:9], v[8:9], 0, s[14:15]
	global_load_dword v106, v[8:9], off
	v_lshl_add_u64 v[8:9], v[8:9], 0, s[14:15]
	global_load_dword v108, v[8:9], off
	v_lshl_add_u64 v[8:9], v[8:9], 0, s[14:15]
	global_load_dword v110, v[8:9], off
	v_lshl_add_u64 v[8:9], v[8:9], 0, s[14:15]
	global_load_dword v112, v[8:9], off
	v_lshl_add_u64 v[8:9], v[8:9], 0, s[14:15]
	global_load_dword v114, v[8:9], off
	v_lshl_add_u64 v[8:9], v[8:9], 0, s[14:15]
	global_load_dword v116, v[8:9], off
	v_lshl_add_u64 v[8:9], v[8:9], 0, s[14:15]
	global_load_dword v118, v[8:9], off
	v_lshl_add_u64 v[8:9], v[8:9], 0, s[14:15]
	global_load_dword v120, v[8:9], off
	v_lshl_add_u64 v[8:9], v[8:9], 0, s[14:15]
	global_load_dword v122, v[8:9], off
	v_lshl_add_u64 v[8:9], v[8:9], 0, s[14:15]
	global_load_dword v124, v[8:9], off
	v_lshl_add_u64 v[8:9], v[8:9], 0, s[14:15]
	global_load_dword v126, v[8:9], off
	v_lshl_add_u64 v[8:9], v[8:9], 0, s[14:15]
	global_load_dword v128, v[8:9], off
	v_lshl_add_u64 v[8:9], v[8:9], 0, s[14:15]
	global_load_dword v130, v[8:9], off
	v_lshl_add_u64 v[8:9], v[8:9], 0, s[14:15]
	global_load_dword v132, v[8:9], off
	v_lshl_add_u64 v[8:9], v[8:9], 0, s[14:15]
	global_load_dword v134, v[8:9], off
	v_lshl_add_u64 v[8:9], v[8:9], 0, s[14:15]
	global_load_dword v136, v[8:9], off
	v_lshl_add_u64 v[8:9], v[8:9], 0, s[14:15]
	global_load_dword v138, v[8:9], off
	v_lshl_add_u64 v[8:9], v[8:9], 0, s[14:15]
	global_load_dword v140, v[8:9], off
	v_lshl_add_u64 v[8:9], v[8:9], 0, s[14:15]
	global_load_dword v142, v[8:9], off
	v_lshl_add_u64 v[8:9], v[8:9], 0, s[14:15]
	global_load_dword v144, v[8:9], off
	v_lshl_add_u64 v[8:9], v[8:9], 0, s[14:15]
	global_load_dword v146, v[8:9], off
	v_lshl_add_u64 v[8:9], v[8:9], 0, s[14:15]
	global_load_dword v148, v[8:9], off
	v_lshl_add_u64 v[8:9], v[8:9], 0, s[14:15]
	global_load_dword v150, v[8:9], off
	v_lshl_add_u64 v[8:9], v[8:9], 0, s[14:15]
	global_load_dword v152, v[8:9], off
	v_lshl_add_u64 v[8:9], v[8:9], 0, s[14:15]
	global_load_dword v154, v[8:9], off
	v_lshl_add_u64 v[8:9], v[8:9], 0, s[14:15]
	global_load_dword v156, v[8:9], off
	v_lshl_add_u64 v[8:9], v[8:9], 0, s[14:15]
	global_load_dword v158, v[8:9], off
	v_lshl_add_u64 v[8:9], v[8:9], 0, s[14:15]
	global_load_dword v164, v[8:9], off
	v_lshl_add_u64 v[8:9], v[8:9], 0, s[14:15]
	global_load_dword v166, v[8:9], off
	v_lshl_add_u64 v[8:9], v[8:9], 0, s[14:15]
	global_load_dword v168, v[8:9], off
	v_lshl_add_u64 v[8:9], v[8:9], 0, s[14:15]
	global_load_dword v170, v[8:9], off
	s_waitcnt vmcnt(63)
	v_readlane_b32 s6, v3, 0
	v_readlane_b32 s7, v19, 0
	v_readlane_b32 s8, v20, 0
	v_readlane_b32 s9, v21, 0
	v_readlane_b32 s10, v22, 0
	v_readlane_b32 s11, v23, 0
	v_readlane_b32 s12, v24, 0
	v_readlane_b32 s13, v25, 0
	v_readlane_b32 s22, v3, 1
	v_readlane_b32 s23, v19, 1
	v_readlane_b32 s24, v20, 1
	v_readlane_b32 s25, v21, 1
	v_readlane_b32 s26, v22, 1
	v_readlane_b32 s27, v23, 1
	v_readlane_b32 s30, v24, 1
	v_readlane_b32 s31, v25, 1
	v_pk_fma_f32 v[16:17], v[40:41], s[6:7], v[16:17] op_sel_hi:[0,1,1]
	v_pk_fma_f32 v[14:15], v[40:41], s[8:9], v[14:15] op_sel_hi:[0,1,1]
	v_pk_fma_f32 v[12:13], v[40:41], s[10:11], v[12:13] op_sel_hi:[0,1,1]
	v_pk_fma_f32 v[10:11], v[40:41], s[12:13], v[10:11] op_sel_hi:[0,1,1]
	v_readlane_b32 s6, v3, 2
	v_readlane_b32 s7, v19, 2
	v_readlane_b32 s8, v20, 2
	v_readlane_b32 s9, v21, 2
	v_readlane_b32 s10, v22, 2
	v_readlane_b32 s11, v23, 2
	v_readlane_b32 s12, v24, 2
	v_readlane_b32 s13, v25, 2
	s_waitcnt vmcnt(62)
	v_pk_fma_f32 v[16:17], v[42:43], s[22:23], v[16:17] op_sel_hi:[0,1,1]
	v_pk_fma_f32 v[14:15], v[42:43], s[24:25], v[14:15] op_sel_hi:[0,1,1]
	v_pk_fma_f32 v[12:13], v[42:43], s[26:27], v[12:13] op_sel_hi:[0,1,1]
	v_pk_fma_f32 v[10:11], v[42:43], s[30:31], v[10:11] op_sel_hi:[0,1,1]
	v_readlane_b32 s22, v3, 3
	v_readlane_b32 s23, v19, 3
	v_readlane_b32 s24, v20, 3
	v_readlane_b32 s25, v21, 3
	v_readlane_b32 s26, v22, 3
	v_readlane_b32 s27, v23, 3
	v_readlane_b32 s30, v24, 3
	v_readlane_b32 s31, v25, 3
	s_waitcnt vmcnt(61)
	v_pk_fma_f32 v[16:17], v[44:45], s[6:7], v[16:17] op_sel_hi:[0,1,1]
	v_pk_fma_f32 v[14:15], v[44:45], s[8:9], v[14:15] op_sel_hi:[0,1,1]
	v_pk_fma_f32 v[12:13], v[44:45], s[10:11], v[12:13] op_sel_hi:[0,1,1]
	v_pk_fma_f32 v[10:11], v[44:45], s[12:13], v[10:11] op_sel_hi:[0,1,1]
	v_readlane_b32 s6, v3, 4
	v_readlane_b32 s7, v19, 4
	v_readlane_b32 s8, v20, 4
	v_readlane_b32 s9, v21, 4
	v_readlane_b32 s10, v22, 4
	v_readlane_b32 s11, v23, 4
	v_readlane_b32 s12, v24, 4
	v_readlane_b32 s13, v25, 4
	s_waitcnt vmcnt(60)
	v_pk_fma_f32 v[16:17], v[46:47], s[22:23], v[16:17] op_sel_hi:[0,1,1]
	v_pk_fma_f32 v[14:15], v[46:47], s[24:25], v[14:15] op_sel_hi:[0,1,1]
	v_pk_fma_f32 v[12:13], v[46:47], s[26:27], v[12:13] op_sel_hi:[0,1,1]
	v_pk_fma_f32 v[10:11], v[46:47], s[30:31], v[10:11] op_sel_hi:[0,1,1]
	v_readlane_b32 s22, v3, 5
	v_readlane_b32 s23, v19, 5
	v_readlane_b32 s24, v20, 5
	v_readlane_b32 s25, v21, 5
	v_readlane_b32 s26, v22, 5
	v_readlane_b32 s27, v23, 5
	v_readlane_b32 s30, v24, 5
	v_readlane_b32 s31, v25, 5
	s_waitcnt vmcnt(59)
	v_pk_fma_f32 v[16:17], v[48:49], s[6:7], v[16:17] op_sel_hi:[0,1,1]
	v_pk_fma_f32 v[14:15], v[48:49], s[8:9], v[14:15] op_sel_hi:[0,1,1]
	v_pk_fma_f32 v[12:13], v[48:49], s[10:11], v[12:13] op_sel_hi:[0,1,1]
	v_pk_fma_f32 v[10:11], v[48:49], s[12:13], v[10:11] op_sel_hi:[0,1,1]
	v_readlane_b32 s6, v3, 6
	v_readlane_b32 s7, v19, 6
	v_readlane_b32 s8, v20, 6
	v_readlane_b32 s9, v21, 6
	v_readlane_b32 s10, v22, 6
	v_readlane_b32 s11, v23, 6
	v_readlane_b32 s12, v24, 6
	v_readlane_b32 s13, v25, 6
	s_waitcnt vmcnt(58)
	v_pk_fma_f32 v[16:17], v[50:51], s[22:23], v[16:17] op_sel_hi:[0,1,1]
	v_pk_fma_f32 v[14:15], v[50:51], s[24:25], v[14:15] op_sel_hi:[0,1,1]
	v_pk_fma_f32 v[12:13], v[50:51], s[26:27], v[12:13] op_sel_hi:[0,1,1]
	v_pk_fma_f32 v[10:11], v[50:51], s[30:31], v[10:11] op_sel_hi:[0,1,1]
	v_readlane_b32 s22, v3, 7
	v_readlane_b32 s23, v19, 7
	v_readlane_b32 s24, v20, 7
	v_readlane_b32 s25, v21, 7
	v_readlane_b32 s26, v22, 7
	v_readlane_b32 s27, v23, 7
	v_readlane_b32 s30, v24, 7
	v_readlane_b32 s31, v25, 7
	s_waitcnt vmcnt(57)
	v_pk_fma_f32 v[16:17], v[52:53], s[6:7], v[16:17] op_sel_hi:[0,1,1]
	v_pk_fma_f32 v[14:15], v[52:53], s[8:9], v[14:15] op_sel_hi:[0,1,1]
	v_pk_fma_f32 v[12:13], v[52:53], s[10:11], v[12:13] op_sel_hi:[0,1,1]
	v_pk_fma_f32 v[10:11], v[52:53], s[12:13], v[10:11] op_sel_hi:[0,1,1]
	v_readlane_b32 s6, v3, 8
	v_readlane_b32 s7, v19, 8
	v_readlane_b32 s8, v20, 8
	v_readlane_b32 s9, v21, 8
	v_readlane_b32 s10, v22, 8
	v_readlane_b32 s11, v23, 8
	v_readlane_b32 s12, v24, 8
	v_readlane_b32 s13, v25, 8
	s_waitcnt vmcnt(56)
	v_pk_fma_f32 v[16:17], v[54:55], s[22:23], v[16:17] op_sel_hi:[0,1,1]
	v_pk_fma_f32 v[14:15], v[54:55], s[24:25], v[14:15] op_sel_hi:[0,1,1]
	v_pk_fma_f32 v[12:13], v[54:55], s[26:27], v[12:13] op_sel_hi:[0,1,1]
	v_pk_fma_f32 v[10:11], v[54:55], s[30:31], v[10:11] op_sel_hi:[0,1,1]
	v_readlane_b32 s22, v3, 9
	v_readlane_b32 s23, v19, 9
	v_readlane_b32 s24, v20, 9
	v_readlane_b32 s25, v21, 9
	v_readlane_b32 s26, v22, 9
	v_readlane_b32 s27, v23, 9
	v_readlane_b32 s30, v24, 9
	v_readlane_b32 s31, v25, 9
	s_waitcnt vmcnt(55)
	v_pk_fma_f32 v[16:17], v[56:57], s[6:7], v[16:17] op_sel_hi:[0,1,1]
	v_pk_fma_f32 v[14:15], v[56:57], s[8:9], v[14:15] op_sel_hi:[0,1,1]
	v_pk_fma_f32 v[12:13], v[56:57], s[10:11], v[12:13] op_sel_hi:[0,1,1]
	v_pk_fma_f32 v[10:11], v[56:57], s[12:13], v[10:11] op_sel_hi:[0,1,1]
	v_readlane_b32 s6, v3, 10
	v_readlane_b32 s7, v19, 10
	v_readlane_b32 s8, v20, 10
	v_readlane_b32 s9, v21, 10
	v_readlane_b32 s10, v22, 10
	v_readlane_b32 s11, v23, 10
	v_readlane_b32 s12, v24, 10
	v_readlane_b32 s13, v25, 10
	s_waitcnt vmcnt(54)
	v_pk_fma_f32 v[16:17], v[58:59], s[22:23], v[16:17] op_sel_hi:[0,1,1]
	v_pk_fma_f32 v[14:15], v[58:59], s[24:25], v[14:15] op_sel_hi:[0,1,1]
	v_pk_fma_f32 v[12:13], v[58:59], s[26:27], v[12:13] op_sel_hi:[0,1,1]
	v_pk_fma_f32 v[10:11], v[58:59], s[30:31], v[10:11] op_sel_hi:[0,1,1]
	v_readlane_b32 s22, v3, 11
	v_readlane_b32 s23, v19, 11
	v_readlane_b32 s24, v20, 11
	v_readlane_b32 s25, v21, 11
	v_readlane_b32 s26, v22, 11
	v_readlane_b32 s27, v23, 11
	v_readlane_b32 s30, v24, 11
	v_readlane_b32 s31, v25, 11
	s_waitcnt vmcnt(53)
	v_pk_fma_f32 v[16:17], v[60:61], s[6:7], v[16:17] op_sel_hi:[0,1,1]
	v_pk_fma_f32 v[14:15], v[60:61], s[8:9], v[14:15] op_sel_hi:[0,1,1]
	v_pk_fma_f32 v[12:13], v[60:61], s[10:11], v[12:13] op_sel_hi:[0,1,1]
	v_pk_fma_f32 v[10:11], v[60:61], s[12:13], v[10:11] op_sel_hi:[0,1,1]
	v_readlane_b32 s6, v3, 12
	v_readlane_b32 s7, v19, 12
	v_readlane_b32 s8, v20, 12
	v_readlane_b32 s9, v21, 12
	v_readlane_b32 s10, v22, 12
	v_readlane_b32 s11, v23, 12
	v_readlane_b32 s12, v24, 12
	v_readlane_b32 s13, v25, 12
	s_waitcnt vmcnt(52)
	v_pk_fma_f32 v[16:17], v[62:63], s[22:23], v[16:17] op_sel_hi:[0,1,1]
	v_pk_fma_f32 v[14:15], v[62:63], s[24:25], v[14:15] op_sel_hi:[0,1,1]
	v_pk_fma_f32 v[12:13], v[62:63], s[26:27], v[12:13] op_sel_hi:[0,1,1]
	v_pk_fma_f32 v[10:11], v[62:63], s[30:31], v[10:11] op_sel_hi:[0,1,1]
	v_readlane_b32 s22, v3, 13
	v_readlane_b32 s23, v19, 13
	v_readlane_b32 s24, v20, 13
	v_readlane_b32 s25, v21, 13
	v_readlane_b32 s26, v22, 13
	v_readlane_b32 s27, v23, 13
	v_readlane_b32 s30, v24, 13
	v_readlane_b32 s31, v25, 13
	s_waitcnt vmcnt(51)
	v_pk_fma_f32 v[16:17], v[64:65], s[6:7], v[16:17] op_sel_hi:[0,1,1]
	v_pk_fma_f32 v[14:15], v[64:65], s[8:9], v[14:15] op_sel_hi:[0,1,1]
	v_pk_fma_f32 v[12:13], v[64:65], s[10:11], v[12:13] op_sel_hi:[0,1,1]
	v_pk_fma_f32 v[10:11], v[64:65], s[12:13], v[10:11] op_sel_hi:[0,1,1]
	v_readlane_b32 s6, v3, 14
	v_readlane_b32 s7, v19, 14
	v_readlane_b32 s8, v20, 14
	v_readlane_b32 s9, v21, 14
	v_readlane_b32 s10, v22, 14
	v_readlane_b32 s11, v23, 14
	v_readlane_b32 s12, v24, 14
	v_readlane_b32 s13, v25, 14
	s_waitcnt vmcnt(50)
	v_pk_fma_f32 v[16:17], v[66:67], s[22:23], v[16:17] op_sel_hi:[0,1,1]
	v_pk_fma_f32 v[14:15], v[66:67], s[24:25], v[14:15] op_sel_hi:[0,1,1]
	v_pk_fma_f32 v[12:13], v[66:67], s[26:27], v[12:13] op_sel_hi:[0,1,1]
	v_pk_fma_f32 v[10:11], v[66:67], s[30:31], v[10:11] op_sel_hi:[0,1,1]
	v_readlane_b32 s22, v3, 15
	v_readlane_b32 s23, v19, 15
	v_readlane_b32 s24, v20, 15
	v_readlane_b32 s25, v21, 15
	v_readlane_b32 s26, v22, 15
	v_readlane_b32 s27, v23, 15
	v_readlane_b32 s30, v24, 15
	v_readlane_b32 s31, v25, 15
	s_waitcnt vmcnt(49)
	v_pk_fma_f32 v[16:17], v[68:69], s[6:7], v[16:17] op_sel_hi:[0,1,1]
	v_pk_fma_f32 v[14:15], v[68:69], s[8:9], v[14:15] op_sel_hi:[0,1,1]
	v_pk_fma_f32 v[12:13], v[68:69], s[10:11], v[12:13] op_sel_hi:[0,1,1]
	v_pk_fma_f32 v[10:11], v[68:69], s[12:13], v[10:11] op_sel_hi:[0,1,1]
	v_readlane_b32 s6, v3, 16
	v_readlane_b32 s7, v19, 16
	v_readlane_b32 s8, v20, 16
	v_readlane_b32 s9, v21, 16
	v_readlane_b32 s10, v22, 16
	v_readlane_b32 s11, v23, 16
	v_readlane_b32 s12, v24, 16
	v_readlane_b32 s13, v25, 16
	s_waitcnt vmcnt(48)
	v_pk_fma_f32 v[16:17], v[70:71], s[22:23], v[16:17] op_sel_hi:[0,1,1]
	v_pk_fma_f32 v[14:15], v[70:71], s[24:25], v[14:15] op_sel_hi:[0,1,1]
	v_pk_fma_f32 v[12:13], v[70:71], s[26:27], v[12:13] op_sel_hi:[0,1,1]
	v_pk_fma_f32 v[10:11], v[70:71], s[30:31], v[10:11] op_sel_hi:[0,1,1]
	v_readlane_b32 s22, v3, 17
	v_readlane_b32 s23, v19, 17
	v_readlane_b32 s24, v20, 17
	v_readlane_b32 s25, v21, 17
	v_readlane_b32 s26, v22, 17
	v_readlane_b32 s27, v23, 17
	v_readlane_b32 s30, v24, 17
	v_readlane_b32 s31, v25, 17
	s_waitcnt vmcnt(47)
	v_pk_fma_f32 v[16:17], v[72:73], s[6:7], v[16:17] op_sel_hi:[0,1,1]
	v_pk_fma_f32 v[14:15], v[72:73], s[8:9], v[14:15] op_sel_hi:[0,1,1]
	v_pk_fma_f32 v[12:13], v[72:73], s[10:11], v[12:13] op_sel_hi:[0,1,1]
	v_pk_fma_f32 v[10:11], v[72:73], s[12:13], v[10:11] op_sel_hi:[0,1,1]
	v_readlane_b32 s6, v3, 18
	v_readlane_b32 s7, v19, 18
	v_readlane_b32 s8, v20, 18
	v_readlane_b32 s9, v21, 18
	v_readlane_b32 s10, v22, 18
	v_readlane_b32 s11, v23, 18
	v_readlane_b32 s12, v24, 18
	v_readlane_b32 s13, v25, 18
	s_waitcnt vmcnt(46)
	v_pk_fma_f32 v[16:17], v[74:75], s[22:23], v[16:17] op_sel_hi:[0,1,1]
	v_pk_fma_f32 v[14:15], v[74:75], s[24:25], v[14:15] op_sel_hi:[0,1,1]
	v_pk_fma_f32 v[12:13], v[74:75], s[26:27], v[12:13] op_sel_hi:[0,1,1]
	v_pk_fma_f32 v[10:11], v[74:75], s[30:31], v[10:11] op_sel_hi:[0,1,1]
	v_readlane_b32 s22, v3, 19
	v_readlane_b32 s23, v19, 19
	v_readlane_b32 s24, v20, 19
	v_readlane_b32 s25, v21, 19
	v_readlane_b32 s26, v22, 19
	v_readlane_b32 s27, v23, 19
	v_readlane_b32 s30, v24, 19
	v_readlane_b32 s31, v25, 19
	s_waitcnt vmcnt(45)
	v_pk_fma_f32 v[16:17], v[76:77], s[6:7], v[16:17] op_sel_hi:[0,1,1]
	v_pk_fma_f32 v[14:15], v[76:77], s[8:9], v[14:15] op_sel_hi:[0,1,1]
	v_pk_fma_f32 v[12:13], v[76:77], s[10:11], v[12:13] op_sel_hi:[0,1,1]
	v_pk_fma_f32 v[10:11], v[76:77], s[12:13], v[10:11] op_sel_hi:[0,1,1]
	v_readlane_b32 s6, v3, 20
	v_readlane_b32 s7, v19, 20
	v_readlane_b32 s8, v20, 20
	v_readlane_b32 s9, v21, 20
	v_readlane_b32 s10, v22, 20
	v_readlane_b32 s11, v23, 20
	v_readlane_b32 s12, v24, 20
	v_readlane_b32 s13, v25, 20
	s_waitcnt vmcnt(44)
	v_pk_fma_f32 v[16:17], v[78:79], s[22:23], v[16:17] op_sel_hi:[0,1,1]
	v_pk_fma_f32 v[14:15], v[78:79], s[24:25], v[14:15] op_sel_hi:[0,1,1]
	v_pk_fma_f32 v[12:13], v[78:79], s[26:27], v[12:13] op_sel_hi:[0,1,1]
	v_pk_fma_f32 v[10:11], v[78:79], s[30:31], v[10:11] op_sel_hi:[0,1,1]
	v_readlane_b32 s22, v3, 21
	v_readlane_b32 s23, v19, 21
	v_readlane_b32 s24, v20, 21
	v_readlane_b32 s25, v21, 21
	v_readlane_b32 s26, v22, 21
	v_readlane_b32 s27, v23, 21
	v_readlane_b32 s30, v24, 21
	v_readlane_b32 s31, v25, 21
	s_waitcnt vmcnt(43)
	v_pk_fma_f32 v[16:17], v[80:81], s[6:7], v[16:17] op_sel_hi:[0,1,1]
	v_pk_fma_f32 v[14:15], v[80:81], s[8:9], v[14:15] op_sel_hi:[0,1,1]
	v_pk_fma_f32 v[12:13], v[80:81], s[10:11], v[12:13] op_sel_hi:[0,1,1]
	v_pk_fma_f32 v[10:11], v[80:81], s[12:13], v[10:11] op_sel_hi:[0,1,1]
	v_readlane_b32 s6, v3, 22
	v_readlane_b32 s7, v19, 22
	v_readlane_b32 s8, v20, 22
	v_readlane_b32 s9, v21, 22
	v_readlane_b32 s10, v22, 22
	v_readlane_b32 s11, v23, 22
	v_readlane_b32 s12, v24, 22
	v_readlane_b32 s13, v25, 22
	s_waitcnt vmcnt(42)
	v_pk_fma_f32 v[16:17], v[82:83], s[22:23], v[16:17] op_sel_hi:[0,1,1]
	v_pk_fma_f32 v[14:15], v[82:83], s[24:25], v[14:15] op_sel_hi:[0,1,1]
	v_pk_fma_f32 v[12:13], v[82:83], s[26:27], v[12:13] op_sel_hi:[0,1,1]
	v_pk_fma_f32 v[10:11], v[82:83], s[30:31], v[10:11] op_sel_hi:[0,1,1]
	v_readlane_b32 s22, v3, 23
	v_readlane_b32 s23, v19, 23
	v_readlane_b32 s24, v20, 23
	v_readlane_b32 s25, v21, 23
	v_readlane_b32 s26, v22, 23
	v_readlane_b32 s27, v23, 23
	v_readlane_b32 s30, v24, 23
	v_readlane_b32 s31, v25, 23
	s_waitcnt vmcnt(41)
	v_pk_fma_f32 v[16:17], v[84:85], s[6:7], v[16:17] op_sel_hi:[0,1,1]
	v_pk_fma_f32 v[14:15], v[84:85], s[8:9], v[14:15] op_sel_hi:[0,1,1]
	v_pk_fma_f32 v[12:13], v[84:85], s[10:11], v[12:13] op_sel_hi:[0,1,1]
	v_pk_fma_f32 v[10:11], v[84:85], s[12:13], v[10:11] op_sel_hi:[0,1,1]
	v_readlane_b32 s6, v3, 24
	v_readlane_b32 s7, v19, 24
	v_readlane_b32 s8, v20, 24
	v_readlane_b32 s9, v21, 24
	v_readlane_b32 s10, v22, 24
	v_readlane_b32 s11, v23, 24
	v_readlane_b32 s12, v24, 24
	v_readlane_b32 s13, v25, 24
	s_waitcnt vmcnt(40)
	v_pk_fma_f32 v[16:17], v[86:87], s[22:23], v[16:17] op_sel_hi:[0,1,1]
	v_pk_fma_f32 v[14:15], v[86:87], s[24:25], v[14:15] op_sel_hi:[0,1,1]
	v_pk_fma_f32 v[12:13], v[86:87], s[26:27], v[12:13] op_sel_hi:[0,1,1]
	v_pk_fma_f32 v[10:11], v[86:87], s[30:31], v[10:11] op_sel_hi:[0,1,1]
	v_readlane_b32 s22, v3, 25
	v_readlane_b32 s23, v19, 25
	v_readlane_b32 s24, v20, 25
	v_readlane_b32 s25, v21, 25
	v_readlane_b32 s26, v22, 25
	v_readlane_b32 s27, v23, 25
	v_readlane_b32 s30, v24, 25
	v_readlane_b32 s31, v25, 25
	s_waitcnt vmcnt(39)
	v_pk_fma_f32 v[16:17], v[88:89], s[6:7], v[16:17] op_sel_hi:[0,1,1]
	v_pk_fma_f32 v[14:15], v[88:89], s[8:9], v[14:15] op_sel_hi:[0,1,1]
	v_pk_fma_f32 v[12:13], v[88:89], s[10:11], v[12:13] op_sel_hi:[0,1,1]
	v_pk_fma_f32 v[10:11], v[88:89], s[12:13], v[10:11] op_sel_hi:[0,1,1]
	v_readlane_b32 s6, v3, 26
	v_readlane_b32 s7, v19, 26
	v_readlane_b32 s8, v20, 26
	v_readlane_b32 s9, v21, 26
	v_readlane_b32 s10, v22, 26
	v_readlane_b32 s11, v23, 26
	v_readlane_b32 s12, v24, 26
	v_readlane_b32 s13, v25, 26
	s_waitcnt vmcnt(38)
	v_pk_fma_f32 v[16:17], v[90:91], s[22:23], v[16:17] op_sel_hi:[0,1,1]
	v_pk_fma_f32 v[14:15], v[90:91], s[24:25], v[14:15] op_sel_hi:[0,1,1]
	v_pk_fma_f32 v[12:13], v[90:91], s[26:27], v[12:13] op_sel_hi:[0,1,1]
	v_pk_fma_f32 v[10:11], v[90:91], s[30:31], v[10:11] op_sel_hi:[0,1,1]
	v_readlane_b32 s22, v3, 27
	v_readlane_b32 s23, v19, 27
	v_readlane_b32 s24, v20, 27
	v_readlane_b32 s25, v21, 27
	v_readlane_b32 s26, v22, 27
	v_readlane_b32 s27, v23, 27
	v_readlane_b32 s30, v24, 27
	v_readlane_b32 s31, v25, 27
	s_waitcnt vmcnt(37)
	v_pk_fma_f32 v[16:17], v[92:93], s[6:7], v[16:17] op_sel_hi:[0,1,1]
	v_pk_fma_f32 v[14:15], v[92:93], s[8:9], v[14:15] op_sel_hi:[0,1,1]
	v_pk_fma_f32 v[12:13], v[92:93], s[10:11], v[12:13] op_sel_hi:[0,1,1]
	v_pk_fma_f32 v[10:11], v[92:93], s[12:13], v[10:11] op_sel_hi:[0,1,1]
	v_readlane_b32 s6, v3, 28
	v_readlane_b32 s7, v19, 28
	v_readlane_b32 s8, v20, 28
	v_readlane_b32 s9, v21, 28
	v_readlane_b32 s10, v22, 28
	v_readlane_b32 s11, v23, 28
	v_readlane_b32 s12, v24, 28
	v_readlane_b32 s13, v25, 28
	s_waitcnt vmcnt(36)
	v_pk_fma_f32 v[16:17], v[94:95], s[22:23], v[16:17] op_sel_hi:[0,1,1]
	v_pk_fma_f32 v[14:15], v[94:95], s[24:25], v[14:15] op_sel_hi:[0,1,1]
	v_pk_fma_f32 v[12:13], v[94:95], s[26:27], v[12:13] op_sel_hi:[0,1,1]
	v_pk_fma_f32 v[10:11], v[94:95], s[30:31], v[10:11] op_sel_hi:[0,1,1]
	v_readlane_b32 s22, v3, 29
	v_readlane_b32 s23, v19, 29
	v_readlane_b32 s24, v20, 29
	v_readlane_b32 s25, v21, 29
	v_readlane_b32 s26, v22, 29
	v_readlane_b32 s27, v23, 29
	v_readlane_b32 s30, v24, 29
	v_readlane_b32 s31, v25, 29
	s_waitcnt vmcnt(35)
	v_pk_fma_f32 v[16:17], v[96:97], s[6:7], v[16:17] op_sel_hi:[0,1,1]
	v_pk_fma_f32 v[14:15], v[96:97], s[8:9], v[14:15] op_sel_hi:[0,1,1]
	v_pk_fma_f32 v[12:13], v[96:97], s[10:11], v[12:13] op_sel_hi:[0,1,1]
	v_pk_fma_f32 v[10:11], v[96:97], s[12:13], v[10:11] op_sel_hi:[0,1,1]
	v_readlane_b32 s6, v3, 30
	v_readlane_b32 s7, v19, 30
	v_readlane_b32 s8, v20, 30
	v_readlane_b32 s9, v21, 30
	v_readlane_b32 s10, v22, 30
	v_readlane_b32 s11, v23, 30
	v_readlane_b32 s12, v24, 30
	v_readlane_b32 s13, v25, 30
	s_waitcnt vmcnt(34)
	v_pk_fma_f32 v[16:17], v[98:99], s[22:23], v[16:17] op_sel_hi:[0,1,1]
	v_pk_fma_f32 v[14:15], v[98:99], s[24:25], v[14:15] op_sel_hi:[0,1,1]
	v_pk_fma_f32 v[12:13], v[98:99], s[26:27], v[12:13] op_sel_hi:[0,1,1]
	v_pk_fma_f32 v[10:11], v[98:99], s[30:31], v[10:11] op_sel_hi:[0,1,1]
	v_readlane_b32 s22, v3, 31
	v_readlane_b32 s23, v19, 31
	v_readlane_b32 s24, v20, 31
	v_readlane_b32 s25, v21, 31
	v_readlane_b32 s26, v22, 31
	v_readlane_b32 s27, v23, 31
	v_readlane_b32 s30, v24, 31
	v_readlane_b32 s31, v25, 31
	s_waitcnt vmcnt(33)
	v_pk_fma_f32 v[16:17], v[100:101], s[6:7], v[16:17] op_sel_hi:[0,1,1]
	v_pk_fma_f32 v[14:15], v[100:101], s[8:9], v[14:15] op_sel_hi:[0,1,1]
	v_pk_fma_f32 v[12:13], v[100:101], s[10:11], v[12:13] op_sel_hi:[0,1,1]
	v_pk_fma_f32 v[10:11], v[100:101], s[12:13], v[10:11] op_sel_hi:[0,1,1]
	v_readlane_b32 s6, v3, 32
	v_readlane_b32 s7, v19, 32
	v_readlane_b32 s8, v20, 32
	v_readlane_b32 s9, v21, 32
	v_readlane_b32 s10, v22, 32
	v_readlane_b32 s11, v23, 32
	v_readlane_b32 s12, v24, 32
	v_readlane_b32 s13, v25, 32
	s_waitcnt vmcnt(32)
	v_pk_fma_f32 v[16:17], v[102:103], s[22:23], v[16:17] op_sel_hi:[0,1,1]
	v_pk_fma_f32 v[14:15], v[102:103], s[24:25], v[14:15] op_sel_hi:[0,1,1]
	v_pk_fma_f32 v[12:13], v[102:103], s[26:27], v[12:13] op_sel_hi:[0,1,1]
	v_pk_fma_f32 v[10:11], v[102:103], s[30:31], v[10:11] op_sel_hi:[0,1,1]
	v_readlane_b32 s22, v3, 33
	v_readlane_b32 s23, v19, 33
	v_readlane_b32 s24, v20, 33
	v_readlane_b32 s25, v21, 33
	v_readlane_b32 s26, v22, 33
	v_readlane_b32 s27, v23, 33
	v_readlane_b32 s30, v24, 33
	v_readlane_b32 s31, v25, 33
	s_waitcnt vmcnt(31)
	v_pk_fma_f32 v[16:17], v[104:105], s[6:7], v[16:17] op_sel_hi:[0,1,1]
	v_pk_fma_f32 v[14:15], v[104:105], s[8:9], v[14:15] op_sel_hi:[0,1,1]
	v_pk_fma_f32 v[12:13], v[104:105], s[10:11], v[12:13] op_sel_hi:[0,1,1]
	v_pk_fma_f32 v[10:11], v[104:105], s[12:13], v[10:11] op_sel_hi:[0,1,1]
	v_readlane_b32 s6, v3, 34
	v_readlane_b32 s7, v19, 34
	v_readlane_b32 s8, v20, 34
	v_readlane_b32 s9, v21, 34
	v_readlane_b32 s10, v22, 34
	v_readlane_b32 s11, v23, 34
	v_readlane_b32 s12, v24, 34
	v_readlane_b32 s13, v25, 34
	s_waitcnt vmcnt(30)
	v_pk_fma_f32 v[16:17], v[106:107], s[22:23], v[16:17] op_sel_hi:[0,1,1]
	v_pk_fma_f32 v[14:15], v[106:107], s[24:25], v[14:15] op_sel_hi:[0,1,1]
	v_pk_fma_f32 v[12:13], v[106:107], s[26:27], v[12:13] op_sel_hi:[0,1,1]
	v_pk_fma_f32 v[10:11], v[106:107], s[30:31], v[10:11] op_sel_hi:[0,1,1]
	v_readlane_b32 s22, v3, 35
	v_readlane_b32 s23, v19, 35
	v_readlane_b32 s24, v20, 35
	v_readlane_b32 s25, v21, 35
	v_readlane_b32 s26, v22, 35
	v_readlane_b32 s27, v23, 35
	v_readlane_b32 s30, v24, 35
	v_readlane_b32 s31, v25, 35
	s_waitcnt vmcnt(29)
	v_pk_fma_f32 v[16:17], v[108:109], s[6:7], v[16:17] op_sel_hi:[0,1,1]
	v_pk_fma_f32 v[14:15], v[108:109], s[8:9], v[14:15] op_sel_hi:[0,1,1]
	v_pk_fma_f32 v[12:13], v[108:109], s[10:11], v[12:13] op_sel_hi:[0,1,1]
	v_pk_fma_f32 v[10:11], v[108:109], s[12:13], v[10:11] op_sel_hi:[0,1,1]
	v_readlane_b32 s6, v3, 36
	v_readlane_b32 s7, v19, 36
	v_readlane_b32 s8, v20, 36
	v_readlane_b32 s9, v21, 36
	v_readlane_b32 s10, v22, 36
	v_readlane_b32 s11, v23, 36
	v_readlane_b32 s12, v24, 36
	v_readlane_b32 s13, v25, 36
	s_waitcnt vmcnt(28)
	v_pk_fma_f32 v[16:17], v[110:111], s[22:23], v[16:17] op_sel_hi:[0,1,1]
	v_pk_fma_f32 v[14:15], v[110:111], s[24:25], v[14:15] op_sel_hi:[0,1,1]
	v_pk_fma_f32 v[12:13], v[110:111], s[26:27], v[12:13] op_sel_hi:[0,1,1]
	v_pk_fma_f32 v[10:11], v[110:111], s[30:31], v[10:11] op_sel_hi:[0,1,1]
	v_readlane_b32 s22, v3, 37
	v_readlane_b32 s23, v19, 37
	v_readlane_b32 s24, v20, 37
	v_readlane_b32 s25, v21, 37
	v_readlane_b32 s26, v22, 37
	v_readlane_b32 s27, v23, 37
	v_readlane_b32 s30, v24, 37
	v_readlane_b32 s31, v25, 37
	s_waitcnt vmcnt(27)
	v_pk_fma_f32 v[16:17], v[112:113], s[6:7], v[16:17] op_sel_hi:[0,1,1]
	v_pk_fma_f32 v[14:15], v[112:113], s[8:9], v[14:15] op_sel_hi:[0,1,1]
	v_pk_fma_f32 v[12:13], v[112:113], s[10:11], v[12:13] op_sel_hi:[0,1,1]
	v_pk_fma_f32 v[10:11], v[112:113], s[12:13], v[10:11] op_sel_hi:[0,1,1]
	v_readlane_b32 s6, v3, 38
	v_readlane_b32 s7, v19, 38
	v_readlane_b32 s8, v20, 38
	v_readlane_b32 s9, v21, 38
	v_readlane_b32 s10, v22, 38
	v_readlane_b32 s11, v23, 38
	v_readlane_b32 s12, v24, 38
	v_readlane_b32 s13, v25, 38
	s_waitcnt vmcnt(26)
	v_pk_fma_f32 v[16:17], v[114:115], s[22:23], v[16:17] op_sel_hi:[0,1,1]
	v_pk_fma_f32 v[14:15], v[114:115], s[24:25], v[14:15] op_sel_hi:[0,1,1]
	v_pk_fma_f32 v[12:13], v[114:115], s[26:27], v[12:13] op_sel_hi:[0,1,1]
	v_pk_fma_f32 v[10:11], v[114:115], s[30:31], v[10:11] op_sel_hi:[0,1,1]
	v_readlane_b32 s22, v3, 39
	v_readlane_b32 s23, v19, 39
	v_readlane_b32 s24, v20, 39
	v_readlane_b32 s25, v21, 39
	v_readlane_b32 s26, v22, 39
	v_readlane_b32 s27, v23, 39
	v_readlane_b32 s30, v24, 39
	v_readlane_b32 s31, v25, 39
	s_waitcnt vmcnt(25)
	v_pk_fma_f32 v[16:17], v[116:117], s[6:7], v[16:17] op_sel_hi:[0,1,1]
	v_pk_fma_f32 v[14:15], v[116:117], s[8:9], v[14:15] op_sel_hi:[0,1,1]
	v_pk_fma_f32 v[12:13], v[116:117], s[10:11], v[12:13] op_sel_hi:[0,1,1]
	v_pk_fma_f32 v[10:11], v[116:117], s[12:13], v[10:11] op_sel_hi:[0,1,1]
	v_readlane_b32 s6, v3, 40
	v_readlane_b32 s7, v19, 40
	v_readlane_b32 s8, v20, 40
	v_readlane_b32 s9, v21, 40
	v_readlane_b32 s10, v22, 40
	v_readlane_b32 s11, v23, 40
	v_readlane_b32 s12, v24, 40
	v_readlane_b32 s13, v25, 40
	s_waitcnt vmcnt(24)
	v_pk_fma_f32 v[16:17], v[118:119], s[22:23], v[16:17] op_sel_hi:[0,1,1]
	v_pk_fma_f32 v[14:15], v[118:119], s[24:25], v[14:15] op_sel_hi:[0,1,1]
	v_pk_fma_f32 v[12:13], v[118:119], s[26:27], v[12:13] op_sel_hi:[0,1,1]
	v_pk_fma_f32 v[10:11], v[118:119], s[30:31], v[10:11] op_sel_hi:[0,1,1]
	v_readlane_b32 s22, v3, 41
	v_readlane_b32 s23, v19, 41
	v_readlane_b32 s24, v20, 41
	v_readlane_b32 s25, v21, 41
	v_readlane_b32 s26, v22, 41
	v_readlane_b32 s27, v23, 41
	v_readlane_b32 s30, v24, 41
	v_readlane_b32 s31, v25, 41
	s_waitcnt vmcnt(23)
	v_pk_fma_f32 v[16:17], v[120:121], s[6:7], v[16:17] op_sel_hi:[0,1,1]
	v_pk_fma_f32 v[14:15], v[120:121], s[8:9], v[14:15] op_sel_hi:[0,1,1]
	v_pk_fma_f32 v[12:13], v[120:121], s[10:11], v[12:13] op_sel_hi:[0,1,1]
	v_pk_fma_f32 v[10:11], v[120:121], s[12:13], v[10:11] op_sel_hi:[0,1,1]
	v_readlane_b32 s6, v3, 42
	v_readlane_b32 s7, v19, 42
	v_readlane_b32 s8, v20, 42
	v_readlane_b32 s9, v21, 42
	v_readlane_b32 s10, v22, 42
	v_readlane_b32 s11, v23, 42
	v_readlane_b32 s12, v24, 42
	v_readlane_b32 s13, v25, 42
	s_waitcnt vmcnt(22)
	v_pk_fma_f32 v[16:17], v[122:123], s[22:23], v[16:17] op_sel_hi:[0,1,1]
	v_pk_fma_f32 v[14:15], v[122:123], s[24:25], v[14:15] op_sel_hi:[0,1,1]
	v_pk_fma_f32 v[12:13], v[122:123], s[26:27], v[12:13] op_sel_hi:[0,1,1]
	v_pk_fma_f32 v[10:11], v[122:123], s[30:31], v[10:11] op_sel_hi:[0,1,1]
	v_readlane_b32 s22, v3, 43
	v_readlane_b32 s23, v19, 43
	v_readlane_b32 s24, v20, 43
	v_readlane_b32 s25, v21, 43
	v_readlane_b32 s26, v22, 43
	v_readlane_b32 s27, v23, 43
	v_readlane_b32 s30, v24, 43
	v_readlane_b32 s31, v25, 43
	s_waitcnt vmcnt(21)
	v_pk_fma_f32 v[16:17], v[124:125], s[6:7], v[16:17] op_sel_hi:[0,1,1]
	v_pk_fma_f32 v[14:15], v[124:125], s[8:9], v[14:15] op_sel_hi:[0,1,1]
	v_pk_fma_f32 v[12:13], v[124:125], s[10:11], v[12:13] op_sel_hi:[0,1,1]
	v_pk_fma_f32 v[10:11], v[124:125], s[12:13], v[10:11] op_sel_hi:[0,1,1]
	v_readlane_b32 s6, v3, 44
	v_readlane_b32 s7, v19, 44
	v_readlane_b32 s8, v20, 44
	v_readlane_b32 s9, v21, 44
	v_readlane_b32 s10, v22, 44
	v_readlane_b32 s11, v23, 44
	v_readlane_b32 s12, v24, 44
	v_readlane_b32 s13, v25, 44
	s_waitcnt vmcnt(20)
	v_pk_fma_f32 v[16:17], v[126:127], s[22:23], v[16:17] op_sel_hi:[0,1,1]
	v_pk_fma_f32 v[14:15], v[126:127], s[24:25], v[14:15] op_sel_hi:[0,1,1]
	v_pk_fma_f32 v[12:13], v[126:127], s[26:27], v[12:13] op_sel_hi:[0,1,1]
	v_pk_fma_f32 v[10:11], v[126:127], s[30:31], v[10:11] op_sel_hi:[0,1,1]
	v_readlane_b32 s22, v3, 45
	v_readlane_b32 s23, v19, 45
	v_readlane_b32 s24, v20, 45
	v_readlane_b32 s25, v21, 45
	v_readlane_b32 s26, v22, 45
	v_readlane_b32 s27, v23, 45
	v_readlane_b32 s30, v24, 45
	v_readlane_b32 s31, v25, 45
	s_waitcnt vmcnt(19)
	v_pk_fma_f32 v[16:17], v[128:129], s[6:7], v[16:17] op_sel_hi:[0,1,1]
	v_pk_fma_f32 v[14:15], v[128:129], s[8:9], v[14:15] op_sel_hi:[0,1,1]
	v_pk_fma_f32 v[12:13], v[128:129], s[10:11], v[12:13] op_sel_hi:[0,1,1]
	v_pk_fma_f32 v[10:11], v[128:129], s[12:13], v[10:11] op_sel_hi:[0,1,1]
	v_readlane_b32 s6, v3, 46
	v_readlane_b32 s7, v19, 46
	v_readlane_b32 s8, v20, 46
	v_readlane_b32 s9, v21, 46
	v_readlane_b32 s10, v22, 46
	v_readlane_b32 s11, v23, 46
	v_readlane_b32 s12, v24, 46
	v_readlane_b32 s13, v25, 46
	s_waitcnt vmcnt(18)
	v_pk_fma_f32 v[16:17], v[130:131], s[22:23], v[16:17] op_sel_hi:[0,1,1]
	v_pk_fma_f32 v[14:15], v[130:131], s[24:25], v[14:15] op_sel_hi:[0,1,1]
	v_pk_fma_f32 v[12:13], v[130:131], s[26:27], v[12:13] op_sel_hi:[0,1,1]
	v_pk_fma_f32 v[10:11], v[130:131], s[30:31], v[10:11] op_sel_hi:[0,1,1]
	v_readlane_b32 s22, v3, 47
	v_readlane_b32 s23, v19, 47
	v_readlane_b32 s24, v20, 47
	v_readlane_b32 s25, v21, 47
	v_readlane_b32 s26, v22, 47
	v_readlane_b32 s27, v23, 47
	v_readlane_b32 s30, v24, 47
	v_readlane_b32 s31, v25, 47
	s_waitcnt vmcnt(17)
	v_pk_fma_f32 v[16:17], v[132:133], s[6:7], v[16:17] op_sel_hi:[0,1,1]
	v_pk_fma_f32 v[14:15], v[132:133], s[8:9], v[14:15] op_sel_hi:[0,1,1]
	v_pk_fma_f32 v[12:13], v[132:133], s[10:11], v[12:13] op_sel_hi:[0,1,1]
	v_pk_fma_f32 v[10:11], v[132:133], s[12:13], v[10:11] op_sel_hi:[0,1,1]
	v_readlane_b32 s6, v3, 48
	v_readlane_b32 s7, v19, 48
	v_readlane_b32 s8, v20, 48
	v_readlane_b32 s9, v21, 48
	v_readlane_b32 s10, v22, 48
	v_readlane_b32 s11, v23, 48
	v_readlane_b32 s12, v24, 48
	v_readlane_b32 s13, v25, 48
	s_waitcnt vmcnt(16)
	v_pk_fma_f32 v[16:17], v[134:135], s[22:23], v[16:17] op_sel_hi:[0,1,1]
	v_pk_fma_f32 v[14:15], v[134:135], s[24:25], v[14:15] op_sel_hi:[0,1,1]
	v_pk_fma_f32 v[12:13], v[134:135], s[26:27], v[12:13] op_sel_hi:[0,1,1]
	v_pk_fma_f32 v[10:11], v[134:135], s[30:31], v[10:11] op_sel_hi:[0,1,1]
	v_readlane_b32 s22, v3, 49
	v_readlane_b32 s23, v19, 49
	v_readlane_b32 s24, v20, 49
	v_readlane_b32 s25, v21, 49
	v_readlane_b32 s26, v22, 49
	v_readlane_b32 s27, v23, 49
	v_readlane_b32 s30, v24, 49
	v_readlane_b32 s31, v25, 49
	s_waitcnt vmcnt(15)
	v_pk_fma_f32 v[16:17], v[136:137], s[6:7], v[16:17] op_sel_hi:[0,1,1]
	v_pk_fma_f32 v[14:15], v[136:137], s[8:9], v[14:15] op_sel_hi:[0,1,1]
	v_pk_fma_f32 v[12:13], v[136:137], s[10:11], v[12:13] op_sel_hi:[0,1,1]
	v_pk_fma_f32 v[10:11], v[136:137], s[12:13], v[10:11] op_sel_hi:[0,1,1]
	v_readlane_b32 s6, v3, 50
	v_readlane_b32 s7, v19, 50
	v_readlane_b32 s8, v20, 50
	v_readlane_b32 s9, v21, 50
	v_readlane_b32 s10, v22, 50
	v_readlane_b32 s11, v23, 50
	v_readlane_b32 s12, v24, 50
	v_readlane_b32 s13, v25, 50
	s_waitcnt vmcnt(14)
	v_pk_fma_f32 v[16:17], v[138:139], s[22:23], v[16:17] op_sel_hi:[0,1,1]
	v_pk_fma_f32 v[14:15], v[138:139], s[24:25], v[14:15] op_sel_hi:[0,1,1]
	v_pk_fma_f32 v[12:13], v[138:139], s[26:27], v[12:13] op_sel_hi:[0,1,1]
	v_pk_fma_f32 v[10:11], v[138:139], s[30:31], v[10:11] op_sel_hi:[0,1,1]
	v_readlane_b32 s22, v3, 51
	v_readlane_b32 s23, v19, 51
	v_readlane_b32 s24, v20, 51
	v_readlane_b32 s25, v21, 51
	v_readlane_b32 s26, v22, 51
	v_readlane_b32 s27, v23, 51
	v_readlane_b32 s30, v24, 51
	v_readlane_b32 s31, v25, 51
	s_waitcnt vmcnt(13)
	v_pk_fma_f32 v[16:17], v[140:141], s[6:7], v[16:17] op_sel_hi:[0,1,1]
	v_pk_fma_f32 v[14:15], v[140:141], s[8:9], v[14:15] op_sel_hi:[0,1,1]
	v_pk_fma_f32 v[12:13], v[140:141], s[10:11], v[12:13] op_sel_hi:[0,1,1]
	v_pk_fma_f32 v[10:11], v[140:141], s[12:13], v[10:11] op_sel_hi:[0,1,1]
	v_readlane_b32 s6, v3, 52
	v_readlane_b32 s7, v19, 52
	v_readlane_b32 s8, v20, 52
	v_readlane_b32 s9, v21, 52
	v_readlane_b32 s10, v22, 52
	v_readlane_b32 s11, v23, 52
	v_readlane_b32 s12, v24, 52
	v_readlane_b32 s13, v25, 52
	s_waitcnt vmcnt(12)
	v_pk_fma_f32 v[16:17], v[142:143], s[22:23], v[16:17] op_sel_hi:[0,1,1]
	v_pk_fma_f32 v[14:15], v[142:143], s[24:25], v[14:15] op_sel_hi:[0,1,1]
	v_pk_fma_f32 v[12:13], v[142:143], s[26:27], v[12:13] op_sel_hi:[0,1,1]
	v_pk_fma_f32 v[10:11], v[142:143], s[30:31], v[10:11] op_sel_hi:[0,1,1]
	v_readlane_b32 s22, v3, 53
	v_readlane_b32 s23, v19, 53
	v_readlane_b32 s24, v20, 53
	v_readlane_b32 s25, v21, 53
	v_readlane_b32 s26, v22, 53
	v_readlane_b32 s27, v23, 53
	v_readlane_b32 s30, v24, 53
	v_readlane_b32 s31, v25, 53
	s_waitcnt vmcnt(11)
	v_pk_fma_f32 v[16:17], v[144:145], s[6:7], v[16:17] op_sel_hi:[0,1,1]
	v_pk_fma_f32 v[14:15], v[144:145], s[8:9], v[14:15] op_sel_hi:[0,1,1]
	v_pk_fma_f32 v[12:13], v[144:145], s[10:11], v[12:13] op_sel_hi:[0,1,1]
	v_pk_fma_f32 v[10:11], v[144:145], s[12:13], v[10:11] op_sel_hi:[0,1,1]
	v_readlane_b32 s6, v3, 54
	v_readlane_b32 s7, v19, 54
	v_readlane_b32 s8, v20, 54
	v_readlane_b32 s9, v21, 54
	v_readlane_b32 s10, v22, 54
	v_readlane_b32 s11, v23, 54
	v_readlane_b32 s12, v24, 54
	v_readlane_b32 s13, v25, 54
	s_waitcnt vmcnt(10)
	v_pk_fma_f32 v[16:17], v[146:147], s[22:23], v[16:17] op_sel_hi:[0,1,1]
	v_pk_fma_f32 v[14:15], v[146:147], s[24:25], v[14:15] op_sel_hi:[0,1,1]
	v_pk_fma_f32 v[12:13], v[146:147], s[26:27], v[12:13] op_sel_hi:[0,1,1]
	v_pk_fma_f32 v[10:11], v[146:147], s[30:31], v[10:11] op_sel_hi:[0,1,1]
	v_readlane_b32 s22, v3, 55
	v_readlane_b32 s23, v19, 55
	v_readlane_b32 s24, v20, 55
	v_readlane_b32 s25, v21, 55
	v_readlane_b32 s26, v22, 55
	v_readlane_b32 s27, v23, 55
	v_readlane_b32 s30, v24, 55
	v_readlane_b32 s31, v25, 55
	s_waitcnt vmcnt(9)
	v_pk_fma_f32 v[16:17], v[148:149], s[6:7], v[16:17] op_sel_hi:[0,1,1]
	v_pk_fma_f32 v[14:15], v[148:149], s[8:9], v[14:15] op_sel_hi:[0,1,1]
	v_pk_fma_f32 v[12:13], v[148:149], s[10:11], v[12:13] op_sel_hi:[0,1,1]
	v_pk_fma_f32 v[10:11], v[148:149], s[12:13], v[10:11] op_sel_hi:[0,1,1]
	v_readlane_b32 s6, v3, 56
	v_readlane_b32 s7, v19, 56
	v_readlane_b32 s8, v20, 56
	v_readlane_b32 s9, v21, 56
	v_readlane_b32 s10, v22, 56
	v_readlane_b32 s11, v23, 56
	v_readlane_b32 s12, v24, 56
	v_readlane_b32 s13, v25, 56
	s_waitcnt vmcnt(8)
	v_pk_fma_f32 v[16:17], v[150:151], s[22:23], v[16:17] op_sel_hi:[0,1,1]
	v_pk_fma_f32 v[14:15], v[150:151], s[24:25], v[14:15] op_sel_hi:[0,1,1]
	v_pk_fma_f32 v[12:13], v[150:151], s[26:27], v[12:13] op_sel_hi:[0,1,1]
	v_pk_fma_f32 v[10:11], v[150:151], s[30:31], v[10:11] op_sel_hi:[0,1,1]
	v_readlane_b32 s22, v3, 57
	v_readlane_b32 s23, v19, 57
	v_readlane_b32 s24, v20, 57
	v_readlane_b32 s25, v21, 57
	v_readlane_b32 s26, v22, 57
	v_readlane_b32 s27, v23, 57
	v_readlane_b32 s30, v24, 57
	v_readlane_b32 s31, v25, 57
	s_waitcnt vmcnt(7)
	v_pk_fma_f32 v[16:17], v[152:153], s[6:7], v[16:17] op_sel_hi:[0,1,1]
	v_pk_fma_f32 v[14:15], v[152:153], s[8:9], v[14:15] op_sel_hi:[0,1,1]
	v_pk_fma_f32 v[12:13], v[152:153], s[10:11], v[12:13] op_sel_hi:[0,1,1]
	v_pk_fma_f32 v[10:11], v[152:153], s[12:13], v[10:11] op_sel_hi:[0,1,1]
	v_readlane_b32 s6, v3, 58
	v_readlane_b32 s7, v19, 58
	v_readlane_b32 s8, v20, 58
	v_readlane_b32 s9, v21, 58
	v_readlane_b32 s10, v22, 58
	v_readlane_b32 s11, v23, 58
	v_readlane_b32 s12, v24, 58
	v_readlane_b32 s13, v25, 58
	s_waitcnt vmcnt(6)
	v_pk_fma_f32 v[16:17], v[154:155], s[22:23], v[16:17] op_sel_hi:[0,1,1]
	v_pk_fma_f32 v[14:15], v[154:155], s[24:25], v[14:15] op_sel_hi:[0,1,1]
	v_pk_fma_f32 v[12:13], v[154:155], s[26:27], v[12:13] op_sel_hi:[0,1,1]
	v_pk_fma_f32 v[10:11], v[154:155], s[30:31], v[10:11] op_sel_hi:[0,1,1]
	v_readlane_b32 s22, v3, 59
	v_readlane_b32 s23, v19, 59
	v_readlane_b32 s24, v20, 59
	v_readlane_b32 s25, v21, 59
	v_readlane_b32 s26, v22, 59
	v_readlane_b32 s27, v23, 59
	v_readlane_b32 s30, v24, 59
	v_readlane_b32 s31, v25, 59
	s_waitcnt vmcnt(5)
	v_pk_fma_f32 v[16:17], v[156:157], s[6:7], v[16:17] op_sel_hi:[0,1,1]
	v_pk_fma_f32 v[14:15], v[156:157], s[8:9], v[14:15] op_sel_hi:[0,1,1]
	v_pk_fma_f32 v[12:13], v[156:157], s[10:11], v[12:13] op_sel_hi:[0,1,1]
	v_pk_fma_f32 v[10:11], v[156:157], s[12:13], v[10:11] op_sel_hi:[0,1,1]
	v_readlane_b32 s6, v3, 60
	v_readlane_b32 s7, v19, 60
	v_readlane_b32 s8, v20, 60
	v_readlane_b32 s9, v21, 60
	v_readlane_b32 s10, v22, 60
	v_readlane_b32 s11, v23, 60
	v_readlane_b32 s12, v24, 60
	v_readlane_b32 s13, v25, 60
	s_waitcnt vmcnt(4)
	v_pk_fma_f32 v[16:17], v[158:159], s[22:23], v[16:17] op_sel_hi:[0,1,1]
	v_pk_fma_f32 v[14:15], v[158:159], s[24:25], v[14:15] op_sel_hi:[0,1,1]
	v_pk_fma_f32 v[12:13], v[158:159], s[26:27], v[12:13] op_sel_hi:[0,1,1]
	v_pk_fma_f32 v[10:11], v[158:159], s[30:31], v[10:11] op_sel_hi:[0,1,1]
	v_readlane_b32 s22, v3, 61
	v_readlane_b32 s23, v19, 61
	v_readlane_b32 s24, v20, 61
	v_readlane_b32 s25, v21, 61
	v_readlane_b32 s26, v22, 61
	v_readlane_b32 s27, v23, 61
	v_readlane_b32 s30, v24, 61
	v_readlane_b32 s31, v25, 61
	s_waitcnt vmcnt(3)
	v_pk_fma_f32 v[16:17], v[164:165], s[6:7], v[16:17] op_sel_hi:[0,1,1]
	v_pk_fma_f32 v[14:15], v[164:165], s[8:9], v[14:15] op_sel_hi:[0,1,1]
	v_pk_fma_f32 v[12:13], v[164:165], s[10:11], v[12:13] op_sel_hi:[0,1,1]
	v_pk_fma_f32 v[10:11], v[164:165], s[12:13], v[10:11] op_sel_hi:[0,1,1]
	v_readlane_b32 s6, v3, 62
	v_readlane_b32 s7, v19, 62
	v_readlane_b32 s8, v20, 62
	v_readlane_b32 s9, v21, 62
	v_readlane_b32 s10, v22, 62
	v_readlane_b32 s11, v23, 62
	v_readlane_b32 s12, v24, 62
	v_readlane_b32 s13, v25, 62
	s_waitcnt vmcnt(2)
	v_pk_fma_f32 v[16:17], v[166:167], s[22:23], v[16:17] op_sel_hi:[0,1,1]
	v_pk_fma_f32 v[14:15], v[166:167], s[24:25], v[14:15] op_sel_hi:[0,1,1]
	v_pk_fma_f32 v[12:13], v[166:167], s[26:27], v[12:13] op_sel_hi:[0,1,1]
	v_pk_fma_f32 v[10:11], v[166:167], s[30:31], v[10:11] op_sel_hi:[0,1,1]
	v_readlane_b32 s22, v3, 63
	v_readlane_b32 s23, v19, 63
	v_readlane_b32 s24, v20, 63
	v_readlane_b32 s25, v21, 63
	v_readlane_b32 s26, v22, 63
	v_readlane_b32 s27, v23, 63
	v_readlane_b32 s30, v24, 63
	v_readlane_b32 s31, v25, 63
	s_waitcnt vmcnt(1)
	v_pk_fma_f32 v[16:17], v[168:169], s[6:7], v[16:17] op_sel_hi:[0,1,1]
	v_pk_fma_f32 v[14:15], v[168:169], s[8:9], v[14:15] op_sel_hi:[0,1,1]
	v_pk_fma_f32 v[12:13], v[168:169], s[10:11], v[12:13] op_sel_hi:[0,1,1]
	v_pk_fma_f32 v[10:11], v[168:169], s[12:13], v[10:11] op_sel_hi:[0,1,1]
	s_waitcnt vmcnt(0)
	v_pk_fma_f32 v[16:17], v[170:171], s[22:23], v[16:17] op_sel_hi:[0,1,1]
	v_pk_fma_f32 v[14:15], v[170:171], s[24:25], v[14:15] op_sel_hi:[0,1,1]
	v_pk_fma_f32 v[12:13], v[170:171], s[26:27], v[12:13] op_sel_hi:[0,1,1]
	v_pk_fma_f32 v[10:11], v[170:171], s[30:31], v[10:11] op_sel_hi:[0,1,1]
	v_lshl_add_u64 v[8:9], v[8:9], 0, s[14:15]
	global_load_dword v40, v[8:9], off
	v_lshl_add_u64 v[8:9], v[8:9], 0, s[14:15]
	global_load_dword v42, v[8:9], off
	v_lshl_add_u64 v[8:9], v[8:9], 0, s[14:15]
	global_load_dword v44, v[8:9], off
	v_lshl_add_u64 v[8:9], v[8:9], 0, s[14:15]
	global_load_dword v46, v[8:9], off
	v_lshl_add_u64 v[8:9], v[8:9], 0, s[14:15]
	global_load_dword v48, v[8:9], off
	v_lshl_add_u64 v[8:9], v[8:9], 0, s[14:15]
	global_load_dword v50, v[8:9], off
	v_lshl_add_u64 v[8:9], v[8:9], 0, s[14:15]
	global_load_dword v52, v[8:9], off
	v_lshl_add_u64 v[8:9], v[8:9], 0, s[14:15]
	global_load_dword v54, v[8:9], off
	v_lshl_add_u64 v[8:9], v[8:9], 0, s[14:15]
	global_load_dword v56, v[8:9], off
	v_lshl_add_u64 v[8:9], v[8:9], 0, s[14:15]
	global_load_dword v58, v[8:9], off
	v_lshl_add_u64 v[8:9], v[8:9], 0, s[14:15]
	global_load_dword v60, v[8:9], off
	v_lshl_add_u64 v[8:9], v[8:9], 0, s[14:15]
	global_load_dword v62, v[8:9], off
	v_lshl_add_u64 v[8:9], v[8:9], 0, s[14:15]
	global_load_dword v64, v[8:9], off
	v_lshl_add_u64 v[8:9], v[8:9], 0, s[14:15]
	global_load_dword v66, v[8:9], off
	v_lshl_add_u64 v[8:9], v[8:9], 0, s[14:15]
	global_load_dword v68, v[8:9], off
	v_lshl_add_u64 v[8:9], v[8:9], 0, s[14:15]
	global_load_dword v70, v[8:9], off
	v_lshl_add_u64 v[8:9], v[8:9], 0, s[14:15]
	global_load_dword v72, v[8:9], off
	v_lshl_add_u64 v[8:9], v[8:9], 0, s[14:15]
	global_load_dword v74, v[8:9], off
	v_lshl_add_u64 v[8:9], v[8:9], 0, s[14:15]
	global_load_dword v76, v[8:9], off
	v_lshl_add_u64 v[8:9], v[8:9], 0, s[14:15]
	global_load_dword v78, v[8:9], off
	v_lshl_add_u64 v[8:9], v[8:9], 0, s[14:15]
	global_load_dword v80, v[8:9], off
	v_lshl_add_u64 v[8:9], v[8:9], 0, s[14:15]
	global_load_dword v82, v[8:9], off
	v_lshl_add_u64 v[8:9], v[8:9], 0, s[14:15]
	global_load_dword v84, v[8:9], off
	v_lshl_add_u64 v[8:9], v[8:9], 0, s[14:15]
	global_load_dword v86, v[8:9], off
	v_lshl_add_u64 v[8:9], v[8:9], 0, s[14:15]
	global_load_dword v88, v[8:9], off
	v_lshl_add_u64 v[8:9], v[8:9], 0, s[14:15]
	global_load_dword v90, v[8:9], off
	v_lshl_add_u64 v[8:9], v[8:9], 0, s[14:15]
	global_load_dword v92, v[8:9], off
	v_lshl_add_u64 v[8:9], v[8:9], 0, s[14:15]
	global_load_dword v94, v[8:9], off
	v_lshl_add_u64 v[8:9], v[8:9], 0, s[14:15]
	global_load_dword v96, v[8:9], off
	v_lshl_add_u64 v[8:9], v[8:9], 0, s[14:15]
	global_load_dword v98, v[8:9], off
	v_lshl_add_u64 v[8:9], v[8:9], 0, s[14:15]
	global_load_dword v100, v[8:9], off
	v_lshl_add_u64 v[8:9], v[8:9], 0, s[14:15]
	global_load_dword v102, v[8:9], off
	v_lshl_add_u64 v[8:9], v[8:9], 0, s[14:15]
	global_load_dword v104, v[8:9], off
	v_lshl_add_u64 v[8:9], v[8:9], 0, s[14:15]
	global_load_dword v106, v[8:9], off
	v_lshl_add_u64 v[8:9], v[8:9], 0, s[14:15]
	global_load_dword v108, v[8:9], off
	v_lshl_add_u64 v[8:9], v[8:9], 0, s[14:15]
	global_load_dword v110, v[8:9], off
	v_lshl_add_u64 v[8:9], v[8:9], 0, s[14:15]
	global_load_dword v112, v[8:9], off
	v_lshl_add_u64 v[8:9], v[8:9], 0, s[14:15]
	global_load_dword v114, v[8:9], off
	v_lshl_add_u64 v[8:9], v[8:9], 0, s[14:15]
	global_load_dword v116, v[8:9], off
	v_lshl_add_u64 v[8:9], v[8:9], 0, s[14:15]
	global_load_dword v118, v[8:9], off
	v_lshl_add_u64 v[8:9], v[8:9], 0, s[14:15]
	global_load_dword v120, v[8:9], off
	v_lshl_add_u64 v[8:9], v[8:9], 0, s[14:15]
	global_load_dword v122, v[8:9], off
	v_lshl_add_u64 v[8:9], v[8:9], 0, s[14:15]
	global_load_dword v124, v[8:9], off
	v_lshl_add_u64 v[8:9], v[8:9], 0, s[14:15]
	global_load_dword v126, v[8:9], off
	v_lshl_add_u64 v[8:9], v[8:9], 0, s[14:15]
	global_load_dword v128, v[8:9], off
	v_lshl_add_u64 v[8:9], v[8:9], 0, s[14:15]
	global_load_dword v130, v[8:9], off
	v_lshl_add_u64 v[8:9], v[8:9], 0, s[14:15]
	global_load_dword v132, v[8:9], off
	v_lshl_add_u64 v[8:9], v[8:9], 0, s[14:15]
	global_load_dword v134, v[8:9], off
	v_lshl_add_u64 v[8:9], v[8:9], 0, s[14:15]
	global_load_dword v136, v[8:9], off
	v_lshl_add_u64 v[8:9], v[8:9], 0, s[14:15]
	global_load_dword v138, v[8:9], off
	v_lshl_add_u64 v[8:9], v[8:9], 0, s[14:15]
	global_load_dword v140, v[8:9], off
	v_lshl_add_u64 v[8:9], v[8:9], 0, s[14:15]
	global_load_dword v142, v[8:9], off
	v_lshl_add_u64 v[8:9], v[8:9], 0, s[14:15]
	global_load_dword v144, v[8:9], off
	v_lshl_add_u64 v[8:9], v[8:9], 0, s[14:15]
	global_load_dword v146, v[8:9], off
	v_lshl_add_u64 v[8:9], v[8:9], 0, s[14:15]
	global_load_dword v148, v[8:9], off
	v_lshl_add_u64 v[8:9], v[8:9], 0, s[14:15]
	global_load_dword v150, v[8:9], off
	v_lshl_add_u64 v[8:9], v[8:9], 0, s[14:15]
	global_load_dword v152, v[8:9], off
	v_lshl_add_u64 v[8:9], v[8:9], 0, s[14:15]
	global_load_dword v154, v[8:9], off
	v_lshl_add_u64 v[8:9], v[8:9], 0, s[14:15]
	global_load_dword v156, v[8:9], off
	v_lshl_add_u64 v[8:9], v[8:9], 0, s[14:15]
	global_load_dword v158, v[8:9], off
	v_lshl_add_u64 v[8:9], v[8:9], 0, s[14:15]
	global_load_dword v164, v[8:9], off
	v_lshl_add_u64 v[8:9], v[8:9], 0, s[14:15]
	global_load_dword v166, v[8:9], off
	v_lshl_add_u64 v[8:9], v[8:9], 0, s[14:15]
	global_load_dword v168, v[8:9], off
	v_lshl_add_u64 v[8:9], v[8:9], 0, s[14:15]
	global_load_dword v170, v[8:9], off
	s_waitcnt vmcnt(63)
	v_readlane_b32 s6, v26, 0
	v_readlane_b32 s7, v27, 0
	v_readlane_b32 s8, v28, 0
	v_readlane_b32 s9, v29, 0
	v_readlane_b32 s10, v30, 0
	v_readlane_b32 s11, v31, 0
	v_readlane_b32 s12, v32, 0
	v_readlane_b32 s13, v33, 0
	v_readlane_b32 s22, v26, 1
	v_readlane_b32 s23, v27, 1
	v_readlane_b32 s24, v28, 1
	v_readlane_b32 s25, v29, 1
	v_readlane_b32 s26, v30, 1
	v_readlane_b32 s27, v31, 1
	v_readlane_b32 s30, v32, 1
	v_readlane_b32 s31, v33, 1
	v_pk_fma_f32 v[16:17], v[40:41], s[6:7], v[16:17] op_sel_hi:[0,1,1]
	v_pk_fma_f32 v[14:15], v[40:41], s[8:9], v[14:15] op_sel_hi:[0,1,1]
	v_pk_fma_f32 v[12:13], v[40:41], s[10:11], v[12:13] op_sel_hi:[0,1,1]
	v_pk_fma_f32 v[10:11], v[40:41], s[12:13], v[10:11] op_sel_hi:[0,1,1]
	v_readlane_b32 s6, v26, 2
	v_readlane_b32 s7, v27, 2
	v_readlane_b32 s8, v28, 2
	v_readlane_b32 s9, v29, 2
	v_readlane_b32 s10, v30, 2
	v_readlane_b32 s11, v31, 2
	v_readlane_b32 s12, v32, 2
	v_readlane_b32 s13, v33, 2
	s_waitcnt vmcnt(62)
	v_pk_fma_f32 v[16:17], v[42:43], s[22:23], v[16:17] op_sel_hi:[0,1,1]
	v_pk_fma_f32 v[14:15], v[42:43], s[24:25], v[14:15] op_sel_hi:[0,1,1]
	v_pk_fma_f32 v[12:13], v[42:43], s[26:27], v[12:13] op_sel_hi:[0,1,1]
	v_pk_fma_f32 v[10:11], v[42:43], s[30:31], v[10:11] op_sel_hi:[0,1,1]
	v_readlane_b32 s22, v26, 3
	v_readlane_b32 s23, v27, 3
	v_readlane_b32 s24, v28, 3
	v_readlane_b32 s25, v29, 3
	v_readlane_b32 s26, v30, 3
	v_readlane_b32 s27, v31, 3
	v_readlane_b32 s30, v32, 3
	v_readlane_b32 s31, v33, 3
	s_waitcnt vmcnt(61)
	v_pk_fma_f32 v[16:17], v[44:45], s[6:7], v[16:17] op_sel_hi:[0,1,1]
	v_pk_fma_f32 v[14:15], v[44:45], s[8:9], v[14:15] op_sel_hi:[0,1,1]
	v_pk_fma_f32 v[12:13], v[44:45], s[10:11], v[12:13] op_sel_hi:[0,1,1]
	v_pk_fma_f32 v[10:11], v[44:45], s[12:13], v[10:11] op_sel_hi:[0,1,1]
	v_readlane_b32 s6, v26, 4
	v_readlane_b32 s7, v27, 4
	v_readlane_b32 s8, v28, 4
	v_readlane_b32 s9, v29, 4
	v_readlane_b32 s10, v30, 4
	v_readlane_b32 s11, v31, 4
	v_readlane_b32 s12, v32, 4
	v_readlane_b32 s13, v33, 4
	s_waitcnt vmcnt(60)
	v_pk_fma_f32 v[16:17], v[46:47], s[22:23], v[16:17] op_sel_hi:[0,1,1]
	v_pk_fma_f32 v[14:15], v[46:47], s[24:25], v[14:15] op_sel_hi:[0,1,1]
	v_pk_fma_f32 v[12:13], v[46:47], s[26:27], v[12:13] op_sel_hi:[0,1,1]
	v_pk_fma_f32 v[10:11], v[46:47], s[30:31], v[10:11] op_sel_hi:[0,1,1]
	v_readlane_b32 s22, v26, 5
	v_readlane_b32 s23, v27, 5
	v_readlane_b32 s24, v28, 5
	v_readlane_b32 s25, v29, 5
	v_readlane_b32 s26, v30, 5
	v_readlane_b32 s27, v31, 5
	v_readlane_b32 s30, v32, 5
	v_readlane_b32 s31, v33, 5
	s_waitcnt vmcnt(59)
	v_pk_fma_f32 v[16:17], v[48:49], s[6:7], v[16:17] op_sel_hi:[0,1,1]
	v_pk_fma_f32 v[14:15], v[48:49], s[8:9], v[14:15] op_sel_hi:[0,1,1]
	v_pk_fma_f32 v[12:13], v[48:49], s[10:11], v[12:13] op_sel_hi:[0,1,1]
	v_pk_fma_f32 v[10:11], v[48:49], s[12:13], v[10:11] op_sel_hi:[0,1,1]
	v_readlane_b32 s6, v26, 6
	v_readlane_b32 s7, v27, 6
	v_readlane_b32 s8, v28, 6
	v_readlane_b32 s9, v29, 6
	v_readlane_b32 s10, v30, 6
	v_readlane_b32 s11, v31, 6
	v_readlane_b32 s12, v32, 6
	v_readlane_b32 s13, v33, 6
	s_waitcnt vmcnt(58)
	v_pk_fma_f32 v[16:17], v[50:51], s[22:23], v[16:17] op_sel_hi:[0,1,1]
	v_pk_fma_f32 v[14:15], v[50:51], s[24:25], v[14:15] op_sel_hi:[0,1,1]
	v_pk_fma_f32 v[12:13], v[50:51], s[26:27], v[12:13] op_sel_hi:[0,1,1]
	v_pk_fma_f32 v[10:11], v[50:51], s[30:31], v[10:11] op_sel_hi:[0,1,1]
	v_readlane_b32 s22, v26, 7
	v_readlane_b32 s23, v27, 7
	v_readlane_b32 s24, v28, 7
	v_readlane_b32 s25, v29, 7
	v_readlane_b32 s26, v30, 7
	v_readlane_b32 s27, v31, 7
	v_readlane_b32 s30, v32, 7
	v_readlane_b32 s31, v33, 7
	s_waitcnt vmcnt(57)
	v_pk_fma_f32 v[16:17], v[52:53], s[6:7], v[16:17] op_sel_hi:[0,1,1]
	v_pk_fma_f32 v[14:15], v[52:53], s[8:9], v[14:15] op_sel_hi:[0,1,1]
	v_pk_fma_f32 v[12:13], v[52:53], s[10:11], v[12:13] op_sel_hi:[0,1,1]
	v_pk_fma_f32 v[10:11], v[52:53], s[12:13], v[10:11] op_sel_hi:[0,1,1]
	v_readlane_b32 s6, v26, 8
	v_readlane_b32 s7, v27, 8
	v_readlane_b32 s8, v28, 8
	v_readlane_b32 s9, v29, 8
	v_readlane_b32 s10, v30, 8
	v_readlane_b32 s11, v31, 8
	v_readlane_b32 s12, v32, 8
	v_readlane_b32 s13, v33, 8
	s_waitcnt vmcnt(56)
	v_pk_fma_f32 v[16:17], v[54:55], s[22:23], v[16:17] op_sel_hi:[0,1,1]
	v_pk_fma_f32 v[14:15], v[54:55], s[24:25], v[14:15] op_sel_hi:[0,1,1]
	v_pk_fma_f32 v[12:13], v[54:55], s[26:27], v[12:13] op_sel_hi:[0,1,1]
	v_pk_fma_f32 v[10:11], v[54:55], s[30:31], v[10:11] op_sel_hi:[0,1,1]
	v_readlane_b32 s22, v26, 9
	v_readlane_b32 s23, v27, 9
	v_readlane_b32 s24, v28, 9
	v_readlane_b32 s25, v29, 9
	v_readlane_b32 s26, v30, 9
	v_readlane_b32 s27, v31, 9
	v_readlane_b32 s30, v32, 9
	v_readlane_b32 s31, v33, 9
	s_waitcnt vmcnt(55)
	v_pk_fma_f32 v[16:17], v[56:57], s[6:7], v[16:17] op_sel_hi:[0,1,1]
	v_pk_fma_f32 v[14:15], v[56:57], s[8:9], v[14:15] op_sel_hi:[0,1,1]
	v_pk_fma_f32 v[12:13], v[56:57], s[10:11], v[12:13] op_sel_hi:[0,1,1]
	v_pk_fma_f32 v[10:11], v[56:57], s[12:13], v[10:11] op_sel_hi:[0,1,1]
	v_readlane_b32 s6, v26, 10
	v_readlane_b32 s7, v27, 10
	v_readlane_b32 s8, v28, 10
	v_readlane_b32 s9, v29, 10
	v_readlane_b32 s10, v30, 10
	v_readlane_b32 s11, v31, 10
	v_readlane_b32 s12, v32, 10
	v_readlane_b32 s13, v33, 10
	s_waitcnt vmcnt(54)
	v_pk_fma_f32 v[16:17], v[58:59], s[22:23], v[16:17] op_sel_hi:[0,1,1]
	v_pk_fma_f32 v[14:15], v[58:59], s[24:25], v[14:15] op_sel_hi:[0,1,1]
	v_pk_fma_f32 v[12:13], v[58:59], s[26:27], v[12:13] op_sel_hi:[0,1,1]
	v_pk_fma_f32 v[10:11], v[58:59], s[30:31], v[10:11] op_sel_hi:[0,1,1]
	v_readlane_b32 s22, v26, 11
	v_readlane_b32 s23, v27, 11
	v_readlane_b32 s24, v28, 11
	v_readlane_b32 s25, v29, 11
	v_readlane_b32 s26, v30, 11
	v_readlane_b32 s27, v31, 11
	v_readlane_b32 s30, v32, 11
	v_readlane_b32 s31, v33, 11
	s_waitcnt vmcnt(53)
	v_pk_fma_f32 v[16:17], v[60:61], s[6:7], v[16:17] op_sel_hi:[0,1,1]
	v_pk_fma_f32 v[14:15], v[60:61], s[8:9], v[14:15] op_sel_hi:[0,1,1]
	v_pk_fma_f32 v[12:13], v[60:61], s[10:11], v[12:13] op_sel_hi:[0,1,1]
	v_pk_fma_f32 v[10:11], v[60:61], s[12:13], v[10:11] op_sel_hi:[0,1,1]
	v_readlane_b32 s6, v26, 12
	v_readlane_b32 s7, v27, 12
	v_readlane_b32 s8, v28, 12
	v_readlane_b32 s9, v29, 12
	v_readlane_b32 s10, v30, 12
	v_readlane_b32 s11, v31, 12
	v_readlane_b32 s12, v32, 12
	v_readlane_b32 s13, v33, 12
	s_waitcnt vmcnt(52)
	v_pk_fma_f32 v[16:17], v[62:63], s[22:23], v[16:17] op_sel_hi:[0,1,1]
	v_pk_fma_f32 v[14:15], v[62:63], s[24:25], v[14:15] op_sel_hi:[0,1,1]
	v_pk_fma_f32 v[12:13], v[62:63], s[26:27], v[12:13] op_sel_hi:[0,1,1]
	v_pk_fma_f32 v[10:11], v[62:63], s[30:31], v[10:11] op_sel_hi:[0,1,1]
	v_readlane_b32 s22, v26, 13
	v_readlane_b32 s23, v27, 13
	v_readlane_b32 s24, v28, 13
	v_readlane_b32 s25, v29, 13
	v_readlane_b32 s26, v30, 13
	v_readlane_b32 s27, v31, 13
	v_readlane_b32 s30, v32, 13
	v_readlane_b32 s31, v33, 13
	s_waitcnt vmcnt(51)
	v_pk_fma_f32 v[16:17], v[64:65], s[6:7], v[16:17] op_sel_hi:[0,1,1]
	v_pk_fma_f32 v[14:15], v[64:65], s[8:9], v[14:15] op_sel_hi:[0,1,1]
	v_pk_fma_f32 v[12:13], v[64:65], s[10:11], v[12:13] op_sel_hi:[0,1,1]
	v_pk_fma_f32 v[10:11], v[64:65], s[12:13], v[10:11] op_sel_hi:[0,1,1]
	v_readlane_b32 s6, v26, 14
	v_readlane_b32 s7, v27, 14
	v_readlane_b32 s8, v28, 14
	v_readlane_b32 s9, v29, 14
	v_readlane_b32 s10, v30, 14
	v_readlane_b32 s11, v31, 14
	v_readlane_b32 s12, v32, 14
	v_readlane_b32 s13, v33, 14
	s_waitcnt vmcnt(50)
	v_pk_fma_f32 v[16:17], v[66:67], s[22:23], v[16:17] op_sel_hi:[0,1,1]
	v_pk_fma_f32 v[14:15], v[66:67], s[24:25], v[14:15] op_sel_hi:[0,1,1]
	v_pk_fma_f32 v[12:13], v[66:67], s[26:27], v[12:13] op_sel_hi:[0,1,1]
	v_pk_fma_f32 v[10:11], v[66:67], s[30:31], v[10:11] op_sel_hi:[0,1,1]
	v_readlane_b32 s22, v26, 15
	v_readlane_b32 s23, v27, 15
	v_readlane_b32 s24, v28, 15
	v_readlane_b32 s25, v29, 15
	v_readlane_b32 s26, v30, 15
	v_readlane_b32 s27, v31, 15
	v_readlane_b32 s30, v32, 15
	v_readlane_b32 s31, v33, 15
	s_waitcnt vmcnt(49)
	v_pk_fma_f32 v[16:17], v[68:69], s[6:7], v[16:17] op_sel_hi:[0,1,1]
	v_pk_fma_f32 v[14:15], v[68:69], s[8:9], v[14:15] op_sel_hi:[0,1,1]
	v_pk_fma_f32 v[12:13], v[68:69], s[10:11], v[12:13] op_sel_hi:[0,1,1]
	v_pk_fma_f32 v[10:11], v[68:69], s[12:13], v[10:11] op_sel_hi:[0,1,1]
	v_readlane_b32 s6, v26, 16
	v_readlane_b32 s7, v27, 16
	v_readlane_b32 s8, v28, 16
	v_readlane_b32 s9, v29, 16
	v_readlane_b32 s10, v30, 16
	v_readlane_b32 s11, v31, 16
	v_readlane_b32 s12, v32, 16
	v_readlane_b32 s13, v33, 16
	s_waitcnt vmcnt(48)
	v_pk_fma_f32 v[16:17], v[70:71], s[22:23], v[16:17] op_sel_hi:[0,1,1]
	v_pk_fma_f32 v[14:15], v[70:71], s[24:25], v[14:15] op_sel_hi:[0,1,1]
	v_pk_fma_f32 v[12:13], v[70:71], s[26:27], v[12:13] op_sel_hi:[0,1,1]
	v_pk_fma_f32 v[10:11], v[70:71], s[30:31], v[10:11] op_sel_hi:[0,1,1]
	v_readlane_b32 s22, v26, 17
	v_readlane_b32 s23, v27, 17
	v_readlane_b32 s24, v28, 17
	v_readlane_b32 s25, v29, 17
	v_readlane_b32 s26, v30, 17
	v_readlane_b32 s27, v31, 17
	v_readlane_b32 s30, v32, 17
	v_readlane_b32 s31, v33, 17
	s_waitcnt vmcnt(47)
	v_pk_fma_f32 v[16:17], v[72:73], s[6:7], v[16:17] op_sel_hi:[0,1,1]
	v_pk_fma_f32 v[14:15], v[72:73], s[8:9], v[14:15] op_sel_hi:[0,1,1]
	v_pk_fma_f32 v[12:13], v[72:73], s[10:11], v[12:13] op_sel_hi:[0,1,1]
	v_pk_fma_f32 v[10:11], v[72:73], s[12:13], v[10:11] op_sel_hi:[0,1,1]
	v_readlane_b32 s6, v26, 18
	v_readlane_b32 s7, v27, 18
	v_readlane_b32 s8, v28, 18
	v_readlane_b32 s9, v29, 18
	v_readlane_b32 s10, v30, 18
	v_readlane_b32 s11, v31, 18
	v_readlane_b32 s12, v32, 18
	v_readlane_b32 s13, v33, 18
	s_waitcnt vmcnt(46)
	v_pk_fma_f32 v[16:17], v[74:75], s[22:23], v[16:17] op_sel_hi:[0,1,1]
	v_pk_fma_f32 v[14:15], v[74:75], s[24:25], v[14:15] op_sel_hi:[0,1,1]
	v_pk_fma_f32 v[12:13], v[74:75], s[26:27], v[12:13] op_sel_hi:[0,1,1]
	v_pk_fma_f32 v[10:11], v[74:75], s[30:31], v[10:11] op_sel_hi:[0,1,1]
	v_readlane_b32 s22, v26, 19
	v_readlane_b32 s23, v27, 19
	v_readlane_b32 s24, v28, 19
	v_readlane_b32 s25, v29, 19
	v_readlane_b32 s26, v30, 19
	v_readlane_b32 s27, v31, 19
	v_readlane_b32 s30, v32, 19
	v_readlane_b32 s31, v33, 19
	s_waitcnt vmcnt(45)
	v_pk_fma_f32 v[16:17], v[76:77], s[6:7], v[16:17] op_sel_hi:[0,1,1]
	v_pk_fma_f32 v[14:15], v[76:77], s[8:9], v[14:15] op_sel_hi:[0,1,1]
	v_pk_fma_f32 v[12:13], v[76:77], s[10:11], v[12:13] op_sel_hi:[0,1,1]
	v_pk_fma_f32 v[10:11], v[76:77], s[12:13], v[10:11] op_sel_hi:[0,1,1]
	v_readlane_b32 s6, v26, 20
	v_readlane_b32 s7, v27, 20
	v_readlane_b32 s8, v28, 20
	v_readlane_b32 s9, v29, 20
	v_readlane_b32 s10, v30, 20
	v_readlane_b32 s11, v31, 20
	v_readlane_b32 s12, v32, 20
	v_readlane_b32 s13, v33, 20
	s_waitcnt vmcnt(44)
	v_pk_fma_f32 v[16:17], v[78:79], s[22:23], v[16:17] op_sel_hi:[0,1,1]
	v_pk_fma_f32 v[14:15], v[78:79], s[24:25], v[14:15] op_sel_hi:[0,1,1]
	v_pk_fma_f32 v[12:13], v[78:79], s[26:27], v[12:13] op_sel_hi:[0,1,1]
	v_pk_fma_f32 v[10:11], v[78:79], s[30:31], v[10:11] op_sel_hi:[0,1,1]
	v_readlane_b32 s22, v26, 21
	v_readlane_b32 s23, v27, 21
	v_readlane_b32 s24, v28, 21
	v_readlane_b32 s25, v29, 21
	v_readlane_b32 s26, v30, 21
	v_readlane_b32 s27, v31, 21
	v_readlane_b32 s30, v32, 21
	v_readlane_b32 s31, v33, 21
	s_waitcnt vmcnt(43)
	v_pk_fma_f32 v[16:17], v[80:81], s[6:7], v[16:17] op_sel_hi:[0,1,1]
	v_pk_fma_f32 v[14:15], v[80:81], s[8:9], v[14:15] op_sel_hi:[0,1,1]
	v_pk_fma_f32 v[12:13], v[80:81], s[10:11], v[12:13] op_sel_hi:[0,1,1]
	v_pk_fma_f32 v[10:11], v[80:81], s[12:13], v[10:11] op_sel_hi:[0,1,1]
	v_readlane_b32 s6, v26, 22
	v_readlane_b32 s7, v27, 22
	v_readlane_b32 s8, v28, 22
	v_readlane_b32 s9, v29, 22
	v_readlane_b32 s10, v30, 22
	v_readlane_b32 s11, v31, 22
	v_readlane_b32 s12, v32, 22
	v_readlane_b32 s13, v33, 22
	s_waitcnt vmcnt(42)
	v_pk_fma_f32 v[16:17], v[82:83], s[22:23], v[16:17] op_sel_hi:[0,1,1]
	v_pk_fma_f32 v[14:15], v[82:83], s[24:25], v[14:15] op_sel_hi:[0,1,1]
	v_pk_fma_f32 v[12:13], v[82:83], s[26:27], v[12:13] op_sel_hi:[0,1,1]
	v_pk_fma_f32 v[10:11], v[82:83], s[30:31], v[10:11] op_sel_hi:[0,1,1]
	v_readlane_b32 s22, v26, 23
	v_readlane_b32 s23, v27, 23
	v_readlane_b32 s24, v28, 23
	v_readlane_b32 s25, v29, 23
	v_readlane_b32 s26, v30, 23
	v_readlane_b32 s27, v31, 23
	v_readlane_b32 s30, v32, 23
	v_readlane_b32 s31, v33, 23
	s_waitcnt vmcnt(41)
	v_pk_fma_f32 v[16:17], v[84:85], s[6:7], v[16:17] op_sel_hi:[0,1,1]
	v_pk_fma_f32 v[14:15], v[84:85], s[8:9], v[14:15] op_sel_hi:[0,1,1]
	v_pk_fma_f32 v[12:13], v[84:85], s[10:11], v[12:13] op_sel_hi:[0,1,1]
	v_pk_fma_f32 v[10:11], v[84:85], s[12:13], v[10:11] op_sel_hi:[0,1,1]
	v_readlane_b32 s6, v26, 24
	v_readlane_b32 s7, v27, 24
	v_readlane_b32 s8, v28, 24
	v_readlane_b32 s9, v29, 24
	v_readlane_b32 s10, v30, 24
	v_readlane_b32 s11, v31, 24
	v_readlane_b32 s12, v32, 24
	v_readlane_b32 s13, v33, 24
	s_waitcnt vmcnt(40)
	v_pk_fma_f32 v[16:17], v[86:87], s[22:23], v[16:17] op_sel_hi:[0,1,1]
	v_pk_fma_f32 v[14:15], v[86:87], s[24:25], v[14:15] op_sel_hi:[0,1,1]
	v_pk_fma_f32 v[12:13], v[86:87], s[26:27], v[12:13] op_sel_hi:[0,1,1]
	v_pk_fma_f32 v[10:11], v[86:87], s[30:31], v[10:11] op_sel_hi:[0,1,1]
	v_readlane_b32 s22, v26, 25
	v_readlane_b32 s23, v27, 25
	v_readlane_b32 s24, v28, 25
	v_readlane_b32 s25, v29, 25
	v_readlane_b32 s26, v30, 25
	v_readlane_b32 s27, v31, 25
	v_readlane_b32 s30, v32, 25
	v_readlane_b32 s31, v33, 25
	s_waitcnt vmcnt(39)
	v_pk_fma_f32 v[16:17], v[88:89], s[6:7], v[16:17] op_sel_hi:[0,1,1]
	v_pk_fma_f32 v[14:15], v[88:89], s[8:9], v[14:15] op_sel_hi:[0,1,1]
	v_pk_fma_f32 v[12:13], v[88:89], s[10:11], v[12:13] op_sel_hi:[0,1,1]
	v_pk_fma_f32 v[10:11], v[88:89], s[12:13], v[10:11] op_sel_hi:[0,1,1]
	v_readlane_b32 s6, v26, 26
	v_readlane_b32 s7, v27, 26
	v_readlane_b32 s8, v28, 26
	v_readlane_b32 s9, v29, 26
	v_readlane_b32 s10, v30, 26
	v_readlane_b32 s11, v31, 26
	v_readlane_b32 s12, v32, 26
	v_readlane_b32 s13, v33, 26
	s_waitcnt vmcnt(38)
	v_pk_fma_f32 v[16:17], v[90:91], s[22:23], v[16:17] op_sel_hi:[0,1,1]
	v_pk_fma_f32 v[14:15], v[90:91], s[24:25], v[14:15] op_sel_hi:[0,1,1]
	v_pk_fma_f32 v[12:13], v[90:91], s[26:27], v[12:13] op_sel_hi:[0,1,1]
	v_pk_fma_f32 v[10:11], v[90:91], s[30:31], v[10:11] op_sel_hi:[0,1,1]
	v_readlane_b32 s22, v26, 27
	v_readlane_b32 s23, v27, 27
	v_readlane_b32 s24, v28, 27
	v_readlane_b32 s25, v29, 27
	v_readlane_b32 s26, v30, 27
	v_readlane_b32 s27, v31, 27
	v_readlane_b32 s30, v32, 27
	v_readlane_b32 s31, v33, 27
	s_waitcnt vmcnt(37)
	v_pk_fma_f32 v[16:17], v[92:93], s[6:7], v[16:17] op_sel_hi:[0,1,1]
	v_pk_fma_f32 v[14:15], v[92:93], s[8:9], v[14:15] op_sel_hi:[0,1,1]
	v_pk_fma_f32 v[12:13], v[92:93], s[10:11], v[12:13] op_sel_hi:[0,1,1]
	v_pk_fma_f32 v[10:11], v[92:93], s[12:13], v[10:11] op_sel_hi:[0,1,1]
	v_readlane_b32 s6, v26, 28
	v_readlane_b32 s7, v27, 28
	v_readlane_b32 s8, v28, 28
	v_readlane_b32 s9, v29, 28
	v_readlane_b32 s10, v30, 28
	v_readlane_b32 s11, v31, 28
	v_readlane_b32 s12, v32, 28
	v_readlane_b32 s13, v33, 28
	s_waitcnt vmcnt(36)
	v_pk_fma_f32 v[16:17], v[94:95], s[22:23], v[16:17] op_sel_hi:[0,1,1]
	v_pk_fma_f32 v[14:15], v[94:95], s[24:25], v[14:15] op_sel_hi:[0,1,1]
	v_pk_fma_f32 v[12:13], v[94:95], s[26:27], v[12:13] op_sel_hi:[0,1,1]
	v_pk_fma_f32 v[10:11], v[94:95], s[30:31], v[10:11] op_sel_hi:[0,1,1]
	v_readlane_b32 s22, v26, 29
	v_readlane_b32 s23, v27, 29
	v_readlane_b32 s24, v28, 29
	v_readlane_b32 s25, v29, 29
	v_readlane_b32 s26, v30, 29
	v_readlane_b32 s27, v31, 29
	v_readlane_b32 s30, v32, 29
	v_readlane_b32 s31, v33, 29
	s_waitcnt vmcnt(35)
	v_pk_fma_f32 v[16:17], v[96:97], s[6:7], v[16:17] op_sel_hi:[0,1,1]
	v_pk_fma_f32 v[14:15], v[96:97], s[8:9], v[14:15] op_sel_hi:[0,1,1]
	v_pk_fma_f32 v[12:13], v[96:97], s[10:11], v[12:13] op_sel_hi:[0,1,1]
	v_pk_fma_f32 v[10:11], v[96:97], s[12:13], v[10:11] op_sel_hi:[0,1,1]
	v_readlane_b32 s6, v26, 30
	v_readlane_b32 s7, v27, 30
	v_readlane_b32 s8, v28, 30
	v_readlane_b32 s9, v29, 30
	v_readlane_b32 s10, v30, 30
	v_readlane_b32 s11, v31, 30
	v_readlane_b32 s12, v32, 30
	v_readlane_b32 s13, v33, 30
	s_waitcnt vmcnt(34)
	v_pk_fma_f32 v[16:17], v[98:99], s[22:23], v[16:17] op_sel_hi:[0,1,1]
	v_pk_fma_f32 v[14:15], v[98:99], s[24:25], v[14:15] op_sel_hi:[0,1,1]
	v_pk_fma_f32 v[12:13], v[98:99], s[26:27], v[12:13] op_sel_hi:[0,1,1]
	v_pk_fma_f32 v[10:11], v[98:99], s[30:31], v[10:11] op_sel_hi:[0,1,1]
	v_readlane_b32 s22, v26, 31
	v_readlane_b32 s23, v27, 31
	v_readlane_b32 s24, v28, 31
	v_readlane_b32 s25, v29, 31
	v_readlane_b32 s26, v30, 31
	v_readlane_b32 s27, v31, 31
	v_readlane_b32 s30, v32, 31
	v_readlane_b32 s31, v33, 31
	s_waitcnt vmcnt(33)
	v_pk_fma_f32 v[16:17], v[100:101], s[6:7], v[16:17] op_sel_hi:[0,1,1]
	v_pk_fma_f32 v[14:15], v[100:101], s[8:9], v[14:15] op_sel_hi:[0,1,1]
	v_pk_fma_f32 v[12:13], v[100:101], s[10:11], v[12:13] op_sel_hi:[0,1,1]
	v_pk_fma_f32 v[10:11], v[100:101], s[12:13], v[10:11] op_sel_hi:[0,1,1]
	v_readlane_b32 s6, v26, 32
	v_readlane_b32 s7, v27, 32
	v_readlane_b32 s8, v28, 32
	v_readlane_b32 s9, v29, 32
	v_readlane_b32 s10, v30, 32
	v_readlane_b32 s11, v31, 32
	v_readlane_b32 s12, v32, 32
	v_readlane_b32 s13, v33, 32
	s_waitcnt vmcnt(32)
	v_pk_fma_f32 v[16:17], v[102:103], s[22:23], v[16:17] op_sel_hi:[0,1,1]
	v_pk_fma_f32 v[14:15], v[102:103], s[24:25], v[14:15] op_sel_hi:[0,1,1]
	v_pk_fma_f32 v[12:13], v[102:103], s[26:27], v[12:13] op_sel_hi:[0,1,1]
	v_pk_fma_f32 v[10:11], v[102:103], s[30:31], v[10:11] op_sel_hi:[0,1,1]
	v_readlane_b32 s22, v26, 33
	v_readlane_b32 s23, v27, 33
	v_readlane_b32 s24, v28, 33
	v_readlane_b32 s25, v29, 33
	v_readlane_b32 s26, v30, 33
	v_readlane_b32 s27, v31, 33
	v_readlane_b32 s30, v32, 33
	v_readlane_b32 s31, v33, 33
	s_waitcnt vmcnt(31)
	v_pk_fma_f32 v[16:17], v[104:105], s[6:7], v[16:17] op_sel_hi:[0,1,1]
	v_pk_fma_f32 v[14:15], v[104:105], s[8:9], v[14:15] op_sel_hi:[0,1,1]
	v_pk_fma_f32 v[12:13], v[104:105], s[10:11], v[12:13] op_sel_hi:[0,1,1]
	v_pk_fma_f32 v[10:11], v[104:105], s[12:13], v[10:11] op_sel_hi:[0,1,1]
	v_readlane_b32 s6, v26, 34
	v_readlane_b32 s7, v27, 34
	v_readlane_b32 s8, v28, 34
	v_readlane_b32 s9, v29, 34
	v_readlane_b32 s10, v30, 34
	v_readlane_b32 s11, v31, 34
	v_readlane_b32 s12, v32, 34
	v_readlane_b32 s13, v33, 34
	s_waitcnt vmcnt(30)
	v_pk_fma_f32 v[16:17], v[106:107], s[22:23], v[16:17] op_sel_hi:[0,1,1]
	v_pk_fma_f32 v[14:15], v[106:107], s[24:25], v[14:15] op_sel_hi:[0,1,1]
	v_pk_fma_f32 v[12:13], v[106:107], s[26:27], v[12:13] op_sel_hi:[0,1,1]
	v_pk_fma_f32 v[10:11], v[106:107], s[30:31], v[10:11] op_sel_hi:[0,1,1]
	v_readlane_b32 s22, v26, 35
	v_readlane_b32 s23, v27, 35
	v_readlane_b32 s24, v28, 35
	v_readlane_b32 s25, v29, 35
	v_readlane_b32 s26, v30, 35
	v_readlane_b32 s27, v31, 35
	v_readlane_b32 s30, v32, 35
	v_readlane_b32 s31, v33, 35
	s_waitcnt vmcnt(29)
	v_pk_fma_f32 v[16:17], v[108:109], s[6:7], v[16:17] op_sel_hi:[0,1,1]
	v_pk_fma_f32 v[14:15], v[108:109], s[8:9], v[14:15] op_sel_hi:[0,1,1]
	v_pk_fma_f32 v[12:13], v[108:109], s[10:11], v[12:13] op_sel_hi:[0,1,1]
	v_pk_fma_f32 v[10:11], v[108:109], s[12:13], v[10:11] op_sel_hi:[0,1,1]
	v_readlane_b32 s6, v26, 36
	v_readlane_b32 s7, v27, 36
	v_readlane_b32 s8, v28, 36
	v_readlane_b32 s9, v29, 36
	v_readlane_b32 s10, v30, 36
	v_readlane_b32 s11, v31, 36
	v_readlane_b32 s12, v32, 36
	v_readlane_b32 s13, v33, 36
	s_waitcnt vmcnt(28)
	v_pk_fma_f32 v[16:17], v[110:111], s[22:23], v[16:17] op_sel_hi:[0,1,1]
	v_pk_fma_f32 v[14:15], v[110:111], s[24:25], v[14:15] op_sel_hi:[0,1,1]
	v_pk_fma_f32 v[12:13], v[110:111], s[26:27], v[12:13] op_sel_hi:[0,1,1]
	v_pk_fma_f32 v[10:11], v[110:111], s[30:31], v[10:11] op_sel_hi:[0,1,1]
	v_readlane_b32 s22, v26, 37
	v_readlane_b32 s23, v27, 37
	v_readlane_b32 s24, v28, 37
	v_readlane_b32 s25, v29, 37
	v_readlane_b32 s26, v30, 37
	v_readlane_b32 s27, v31, 37
	v_readlane_b32 s30, v32, 37
	v_readlane_b32 s31, v33, 37
	s_waitcnt vmcnt(27)
	v_pk_fma_f32 v[16:17], v[112:113], s[6:7], v[16:17] op_sel_hi:[0,1,1]
	v_pk_fma_f32 v[14:15], v[112:113], s[8:9], v[14:15] op_sel_hi:[0,1,1]
	v_pk_fma_f32 v[12:13], v[112:113], s[10:11], v[12:13] op_sel_hi:[0,1,1]
	v_pk_fma_f32 v[10:11], v[112:113], s[12:13], v[10:11] op_sel_hi:[0,1,1]
	v_readlane_b32 s6, v26, 38
	v_readlane_b32 s7, v27, 38
	v_readlane_b32 s8, v28, 38
	v_readlane_b32 s9, v29, 38
	v_readlane_b32 s10, v30, 38
	v_readlane_b32 s11, v31, 38
	v_readlane_b32 s12, v32, 38
	v_readlane_b32 s13, v33, 38
	s_waitcnt vmcnt(26)
	v_pk_fma_f32 v[16:17], v[114:115], s[22:23], v[16:17] op_sel_hi:[0,1,1]
	v_pk_fma_f32 v[14:15], v[114:115], s[24:25], v[14:15] op_sel_hi:[0,1,1]
	v_pk_fma_f32 v[12:13], v[114:115], s[26:27], v[12:13] op_sel_hi:[0,1,1]
	v_pk_fma_f32 v[10:11], v[114:115], s[30:31], v[10:11] op_sel_hi:[0,1,1]
	v_readlane_b32 s22, v26, 39
	v_readlane_b32 s23, v27, 39
	v_readlane_b32 s24, v28, 39
	v_readlane_b32 s25, v29, 39
	v_readlane_b32 s26, v30, 39
	v_readlane_b32 s27, v31, 39
	v_readlane_b32 s30, v32, 39
	v_readlane_b32 s31, v33, 39
	s_waitcnt vmcnt(25)
	v_pk_fma_f32 v[16:17], v[116:117], s[6:7], v[16:17] op_sel_hi:[0,1,1]
	v_pk_fma_f32 v[14:15], v[116:117], s[8:9], v[14:15] op_sel_hi:[0,1,1]
	v_pk_fma_f32 v[12:13], v[116:117], s[10:11], v[12:13] op_sel_hi:[0,1,1]
	v_pk_fma_f32 v[10:11], v[116:117], s[12:13], v[10:11] op_sel_hi:[0,1,1]
	v_readlane_b32 s6, v26, 40
	v_readlane_b32 s7, v27, 40
	v_readlane_b32 s8, v28, 40
	v_readlane_b32 s9, v29, 40
	v_readlane_b32 s10, v30, 40
	v_readlane_b32 s11, v31, 40
	v_readlane_b32 s12, v32, 40
	v_readlane_b32 s13, v33, 40
	s_waitcnt vmcnt(24)
	v_pk_fma_f32 v[16:17], v[118:119], s[22:23], v[16:17] op_sel_hi:[0,1,1]
	v_pk_fma_f32 v[14:15], v[118:119], s[24:25], v[14:15] op_sel_hi:[0,1,1]
	v_pk_fma_f32 v[12:13], v[118:119], s[26:27], v[12:13] op_sel_hi:[0,1,1]
	v_pk_fma_f32 v[10:11], v[118:119], s[30:31], v[10:11] op_sel_hi:[0,1,1]
	v_readlane_b32 s22, v26, 41
	v_readlane_b32 s23, v27, 41
	v_readlane_b32 s24, v28, 41
	v_readlane_b32 s25, v29, 41
	v_readlane_b32 s26, v30, 41
	v_readlane_b32 s27, v31, 41
	v_readlane_b32 s30, v32, 41
	v_readlane_b32 s31, v33, 41
	s_waitcnt vmcnt(23)
	v_pk_fma_f32 v[16:17], v[120:121], s[6:7], v[16:17] op_sel_hi:[0,1,1]
	v_pk_fma_f32 v[14:15], v[120:121], s[8:9], v[14:15] op_sel_hi:[0,1,1]
	v_pk_fma_f32 v[12:13], v[120:121], s[10:11], v[12:13] op_sel_hi:[0,1,1]
	v_pk_fma_f32 v[10:11], v[120:121], s[12:13], v[10:11] op_sel_hi:[0,1,1]
	v_readlane_b32 s6, v26, 42
	v_readlane_b32 s7, v27, 42
	v_readlane_b32 s8, v28, 42
	v_readlane_b32 s9, v29, 42
	v_readlane_b32 s10, v30, 42
	v_readlane_b32 s11, v31, 42
	v_readlane_b32 s12, v32, 42
	v_readlane_b32 s13, v33, 42
	s_waitcnt vmcnt(22)
	v_pk_fma_f32 v[16:17], v[122:123], s[22:23], v[16:17] op_sel_hi:[0,1,1]
	v_pk_fma_f32 v[14:15], v[122:123], s[24:25], v[14:15] op_sel_hi:[0,1,1]
	v_pk_fma_f32 v[12:13], v[122:123], s[26:27], v[12:13] op_sel_hi:[0,1,1]
	v_pk_fma_f32 v[10:11], v[122:123], s[30:31], v[10:11] op_sel_hi:[0,1,1]
	v_readlane_b32 s22, v26, 43
	v_readlane_b32 s23, v27, 43
	v_readlane_b32 s24, v28, 43
	v_readlane_b32 s25, v29, 43
	v_readlane_b32 s26, v30, 43
	v_readlane_b32 s27, v31, 43
	v_readlane_b32 s30, v32, 43
	v_readlane_b32 s31, v33, 43
	s_waitcnt vmcnt(21)
	v_pk_fma_f32 v[16:17], v[124:125], s[6:7], v[16:17] op_sel_hi:[0,1,1]
	v_pk_fma_f32 v[14:15], v[124:125], s[8:9], v[14:15] op_sel_hi:[0,1,1]
	v_pk_fma_f32 v[12:13], v[124:125], s[10:11], v[12:13] op_sel_hi:[0,1,1]
	v_pk_fma_f32 v[10:11], v[124:125], s[12:13], v[10:11] op_sel_hi:[0,1,1]
	v_readlane_b32 s6, v26, 44
	v_readlane_b32 s7, v27, 44
	v_readlane_b32 s8, v28, 44
	v_readlane_b32 s9, v29, 44
	v_readlane_b32 s10, v30, 44
	v_readlane_b32 s11, v31, 44
	v_readlane_b32 s12, v32, 44
	v_readlane_b32 s13, v33, 44
	s_waitcnt vmcnt(20)
	v_pk_fma_f32 v[16:17], v[126:127], s[22:23], v[16:17] op_sel_hi:[0,1,1]
	v_pk_fma_f32 v[14:15], v[126:127], s[24:25], v[14:15] op_sel_hi:[0,1,1]
	v_pk_fma_f32 v[12:13], v[126:127], s[26:27], v[12:13] op_sel_hi:[0,1,1]
	v_pk_fma_f32 v[10:11], v[126:127], s[30:31], v[10:11] op_sel_hi:[0,1,1]
	v_readlane_b32 s22, v26, 45
	v_readlane_b32 s23, v27, 45
	v_readlane_b32 s24, v28, 45
	v_readlane_b32 s25, v29, 45
	v_readlane_b32 s26, v30, 45
	v_readlane_b32 s27, v31, 45
	v_readlane_b32 s30, v32, 45
	v_readlane_b32 s31, v33, 45
	s_waitcnt vmcnt(19)
	v_pk_fma_f32 v[16:17], v[128:129], s[6:7], v[16:17] op_sel_hi:[0,1,1]
	v_pk_fma_f32 v[14:15], v[128:129], s[8:9], v[14:15] op_sel_hi:[0,1,1]
	v_pk_fma_f32 v[12:13], v[128:129], s[10:11], v[12:13] op_sel_hi:[0,1,1]
	v_pk_fma_f32 v[10:11], v[128:129], s[12:13], v[10:11] op_sel_hi:[0,1,1]
	v_readlane_b32 s6, v26, 46
	v_readlane_b32 s7, v27, 46
	v_readlane_b32 s8, v28, 46
	v_readlane_b32 s9, v29, 46
	v_readlane_b32 s10, v30, 46
	v_readlane_b32 s11, v31, 46
	v_readlane_b32 s12, v32, 46
	v_readlane_b32 s13, v33, 46
	s_waitcnt vmcnt(18)
	v_pk_fma_f32 v[16:17], v[130:131], s[22:23], v[16:17] op_sel_hi:[0,1,1]
	v_pk_fma_f32 v[14:15], v[130:131], s[24:25], v[14:15] op_sel_hi:[0,1,1]
	v_pk_fma_f32 v[12:13], v[130:131], s[26:27], v[12:13] op_sel_hi:[0,1,1]
	v_pk_fma_f32 v[10:11], v[130:131], s[30:31], v[10:11] op_sel_hi:[0,1,1]
	v_readlane_b32 s22, v26, 47
	v_readlane_b32 s23, v27, 47
	v_readlane_b32 s24, v28, 47
	v_readlane_b32 s25, v29, 47
	v_readlane_b32 s26, v30, 47
	v_readlane_b32 s27, v31, 47
	v_readlane_b32 s30, v32, 47
	v_readlane_b32 s31, v33, 47
	s_waitcnt vmcnt(17)
	v_pk_fma_f32 v[16:17], v[132:133], s[6:7], v[16:17] op_sel_hi:[0,1,1]
	v_pk_fma_f32 v[14:15], v[132:133], s[8:9], v[14:15] op_sel_hi:[0,1,1]
	v_pk_fma_f32 v[12:13], v[132:133], s[10:11], v[12:13] op_sel_hi:[0,1,1]
	v_pk_fma_f32 v[10:11], v[132:133], s[12:13], v[10:11] op_sel_hi:[0,1,1]
	v_readlane_b32 s6, v26, 48
	v_readlane_b32 s7, v27, 48
	v_readlane_b32 s8, v28, 48
	v_readlane_b32 s9, v29, 48
	v_readlane_b32 s10, v30, 48
	v_readlane_b32 s11, v31, 48
	v_readlane_b32 s12, v32, 48
	v_readlane_b32 s13, v33, 48
	s_waitcnt vmcnt(16)
	v_pk_fma_f32 v[16:17], v[134:135], s[22:23], v[16:17] op_sel_hi:[0,1,1]
	v_pk_fma_f32 v[14:15], v[134:135], s[24:25], v[14:15] op_sel_hi:[0,1,1]
	v_pk_fma_f32 v[12:13], v[134:135], s[26:27], v[12:13] op_sel_hi:[0,1,1]
	v_pk_fma_f32 v[10:11], v[134:135], s[30:31], v[10:11] op_sel_hi:[0,1,1]
	v_readlane_b32 s22, v26, 49
	v_readlane_b32 s23, v27, 49
	v_readlane_b32 s24, v28, 49
	v_readlane_b32 s25, v29, 49
	v_readlane_b32 s26, v30, 49
	v_readlane_b32 s27, v31, 49
	v_readlane_b32 s30, v32, 49
	v_readlane_b32 s31, v33, 49
	s_waitcnt vmcnt(15)
	v_pk_fma_f32 v[16:17], v[136:137], s[6:7], v[16:17] op_sel_hi:[0,1,1]
	v_pk_fma_f32 v[14:15], v[136:137], s[8:9], v[14:15] op_sel_hi:[0,1,1]
	v_pk_fma_f32 v[12:13], v[136:137], s[10:11], v[12:13] op_sel_hi:[0,1,1]
	v_pk_fma_f32 v[10:11], v[136:137], s[12:13], v[10:11] op_sel_hi:[0,1,1]
	v_readlane_b32 s6, v26, 50
	v_readlane_b32 s7, v27, 50
	v_readlane_b32 s8, v28, 50
	v_readlane_b32 s9, v29, 50
	v_readlane_b32 s10, v30, 50
	v_readlane_b32 s11, v31, 50
	v_readlane_b32 s12, v32, 50
	v_readlane_b32 s13, v33, 50
	s_waitcnt vmcnt(14)
	v_pk_fma_f32 v[16:17], v[138:139], s[22:23], v[16:17] op_sel_hi:[0,1,1]
	v_pk_fma_f32 v[14:15], v[138:139], s[24:25], v[14:15] op_sel_hi:[0,1,1]
	v_pk_fma_f32 v[12:13], v[138:139], s[26:27], v[12:13] op_sel_hi:[0,1,1]
	v_pk_fma_f32 v[10:11], v[138:139], s[30:31], v[10:11] op_sel_hi:[0,1,1]
	v_readlane_b32 s22, v26, 51
	v_readlane_b32 s23, v27, 51
	v_readlane_b32 s24, v28, 51
	v_readlane_b32 s25, v29, 51
	v_readlane_b32 s26, v30, 51
	v_readlane_b32 s27, v31, 51
	v_readlane_b32 s30, v32, 51
	v_readlane_b32 s31, v33, 51
	s_waitcnt vmcnt(13)
	v_pk_fma_f32 v[16:17], v[140:141], s[6:7], v[16:17] op_sel_hi:[0,1,1]
	v_pk_fma_f32 v[14:15], v[140:141], s[8:9], v[14:15] op_sel_hi:[0,1,1]
	v_pk_fma_f32 v[12:13], v[140:141], s[10:11], v[12:13] op_sel_hi:[0,1,1]
	v_pk_fma_f32 v[10:11], v[140:141], s[12:13], v[10:11] op_sel_hi:[0,1,1]
	v_readlane_b32 s6, v26, 52
	v_readlane_b32 s7, v27, 52
	v_readlane_b32 s8, v28, 52
	v_readlane_b32 s9, v29, 52
	v_readlane_b32 s10, v30, 52
	v_readlane_b32 s11, v31, 52
	v_readlane_b32 s12, v32, 52
	v_readlane_b32 s13, v33, 52
	s_waitcnt vmcnt(12)
	v_pk_fma_f32 v[16:17], v[142:143], s[22:23], v[16:17] op_sel_hi:[0,1,1]
	v_pk_fma_f32 v[14:15], v[142:143], s[24:25], v[14:15] op_sel_hi:[0,1,1]
	v_pk_fma_f32 v[12:13], v[142:143], s[26:27], v[12:13] op_sel_hi:[0,1,1]
	v_pk_fma_f32 v[10:11], v[142:143], s[30:31], v[10:11] op_sel_hi:[0,1,1]
	v_readlane_b32 s22, v26, 53
	v_readlane_b32 s23, v27, 53
	v_readlane_b32 s24, v28, 53
	v_readlane_b32 s25, v29, 53
	v_readlane_b32 s26, v30, 53
	v_readlane_b32 s27, v31, 53
	v_readlane_b32 s30, v32, 53
	v_readlane_b32 s31, v33, 53
	s_waitcnt vmcnt(11)
	v_pk_fma_f32 v[16:17], v[144:145], s[6:7], v[16:17] op_sel_hi:[0,1,1]
	v_pk_fma_f32 v[14:15], v[144:145], s[8:9], v[14:15] op_sel_hi:[0,1,1]
	v_pk_fma_f32 v[12:13], v[144:145], s[10:11], v[12:13] op_sel_hi:[0,1,1]
	v_pk_fma_f32 v[10:11], v[144:145], s[12:13], v[10:11] op_sel_hi:[0,1,1]
	v_readlane_b32 s6, v26, 54
	v_readlane_b32 s7, v27, 54
	v_readlane_b32 s8, v28, 54
	v_readlane_b32 s9, v29, 54
	v_readlane_b32 s10, v30, 54
	v_readlane_b32 s11, v31, 54
	v_readlane_b32 s12, v32, 54
	v_readlane_b32 s13, v33, 54
	s_waitcnt vmcnt(10)
	v_pk_fma_f32 v[16:17], v[146:147], s[22:23], v[16:17] op_sel_hi:[0,1,1]
	v_pk_fma_f32 v[14:15], v[146:147], s[24:25], v[14:15] op_sel_hi:[0,1,1]
	v_pk_fma_f32 v[12:13], v[146:147], s[26:27], v[12:13] op_sel_hi:[0,1,1]
	v_pk_fma_f32 v[10:11], v[146:147], s[30:31], v[10:11] op_sel_hi:[0,1,1]
	v_readlane_b32 s22, v26, 55
	v_readlane_b32 s23, v27, 55
	v_readlane_b32 s24, v28, 55
	v_readlane_b32 s25, v29, 55
	v_readlane_b32 s26, v30, 55
	v_readlane_b32 s27, v31, 55
	v_readlane_b32 s30, v32, 55
	v_readlane_b32 s31, v33, 55
	s_waitcnt vmcnt(9)
	v_pk_fma_f32 v[16:17], v[148:149], s[6:7], v[16:17] op_sel_hi:[0,1,1]
	v_pk_fma_f32 v[14:15], v[148:149], s[8:9], v[14:15] op_sel_hi:[0,1,1]
	v_pk_fma_f32 v[12:13], v[148:149], s[10:11], v[12:13] op_sel_hi:[0,1,1]
	v_pk_fma_f32 v[10:11], v[148:149], s[12:13], v[10:11] op_sel_hi:[0,1,1]
	v_readlane_b32 s6, v26, 56
	v_readlane_b32 s7, v27, 56
	v_readlane_b32 s8, v28, 56
	v_readlane_b32 s9, v29, 56
	v_readlane_b32 s10, v30, 56
	v_readlane_b32 s11, v31, 56
	v_readlane_b32 s12, v32, 56
	v_readlane_b32 s13, v33, 56
	s_waitcnt vmcnt(8)
	v_pk_fma_f32 v[16:17], v[150:151], s[22:23], v[16:17] op_sel_hi:[0,1,1]
	v_pk_fma_f32 v[14:15], v[150:151], s[24:25], v[14:15] op_sel_hi:[0,1,1]
	v_pk_fma_f32 v[12:13], v[150:151], s[26:27], v[12:13] op_sel_hi:[0,1,1]
	v_pk_fma_f32 v[10:11], v[150:151], s[30:31], v[10:11] op_sel_hi:[0,1,1]
	v_readlane_b32 s22, v26, 57
	v_readlane_b32 s23, v27, 57
	v_readlane_b32 s24, v28, 57
	v_readlane_b32 s25, v29, 57
	v_readlane_b32 s26, v30, 57
	v_readlane_b32 s27, v31, 57
	v_readlane_b32 s30, v32, 57
	v_readlane_b32 s31, v33, 57
	s_waitcnt vmcnt(7)
	v_pk_fma_f32 v[16:17], v[152:153], s[6:7], v[16:17] op_sel_hi:[0,1,1]
	v_pk_fma_f32 v[14:15], v[152:153], s[8:9], v[14:15] op_sel_hi:[0,1,1]
	v_pk_fma_f32 v[12:13], v[152:153], s[10:11], v[12:13] op_sel_hi:[0,1,1]
	v_pk_fma_f32 v[10:11], v[152:153], s[12:13], v[10:11] op_sel_hi:[0,1,1]
	v_readlane_b32 s6, v26, 58
	v_readlane_b32 s7, v27, 58
	v_readlane_b32 s8, v28, 58
	v_readlane_b32 s9, v29, 58
	v_readlane_b32 s10, v30, 58
	v_readlane_b32 s11, v31, 58
	v_readlane_b32 s12, v32, 58
	v_readlane_b32 s13, v33, 58
	s_waitcnt vmcnt(6)
	v_pk_fma_f32 v[16:17], v[154:155], s[22:23], v[16:17] op_sel_hi:[0,1,1]
	v_pk_fma_f32 v[14:15], v[154:155], s[24:25], v[14:15] op_sel_hi:[0,1,1]
	v_pk_fma_f32 v[12:13], v[154:155], s[26:27], v[12:13] op_sel_hi:[0,1,1]
	v_pk_fma_f32 v[10:11], v[154:155], s[30:31], v[10:11] op_sel_hi:[0,1,1]
	v_readlane_b32 s22, v26, 59
	v_readlane_b32 s23, v27, 59
	v_readlane_b32 s24, v28, 59
	v_readlane_b32 s25, v29, 59
	v_readlane_b32 s26, v30, 59
	v_readlane_b32 s27, v31, 59
	v_readlane_b32 s30, v32, 59
	v_readlane_b32 s31, v33, 59
	s_waitcnt vmcnt(5)
	v_pk_fma_f32 v[16:17], v[156:157], s[6:7], v[16:17] op_sel_hi:[0,1,1]
	v_pk_fma_f32 v[14:15], v[156:157], s[8:9], v[14:15] op_sel_hi:[0,1,1]
	v_pk_fma_f32 v[12:13], v[156:157], s[10:11], v[12:13] op_sel_hi:[0,1,1]
	v_pk_fma_f32 v[10:11], v[156:157], s[12:13], v[10:11] op_sel_hi:[0,1,1]
	v_readlane_b32 s6, v26, 60
	v_readlane_b32 s7, v27, 60
	v_readlane_b32 s8, v28, 60
	v_readlane_b32 s9, v29, 60
	v_readlane_b32 s10, v30, 60
	v_readlane_b32 s11, v31, 60
	v_readlane_b32 s12, v32, 60
	v_readlane_b32 s13, v33, 60
	s_waitcnt vmcnt(4)
	v_pk_fma_f32 v[16:17], v[158:159], s[22:23], v[16:17] op_sel_hi:[0,1,1]
	v_pk_fma_f32 v[14:15], v[158:159], s[24:25], v[14:15] op_sel_hi:[0,1,1]
	v_pk_fma_f32 v[12:13], v[158:159], s[26:27], v[12:13] op_sel_hi:[0,1,1]
	v_pk_fma_f32 v[10:11], v[158:159], s[30:31], v[10:11] op_sel_hi:[0,1,1]
	v_readlane_b32 s22, v26, 61
	v_readlane_b32 s23, v27, 61
	v_readlane_b32 s24, v28, 61
	v_readlane_b32 s25, v29, 61
	v_readlane_b32 s26, v30, 61
	v_readlane_b32 s27, v31, 61
	v_readlane_b32 s30, v32, 61
	v_readlane_b32 s31, v33, 61
	s_waitcnt vmcnt(3)
	v_pk_fma_f32 v[16:17], v[164:165], s[6:7], v[16:17] op_sel_hi:[0,1,1]
	v_pk_fma_f32 v[14:15], v[164:165], s[8:9], v[14:15] op_sel_hi:[0,1,1]
	v_pk_fma_f32 v[12:13], v[164:165], s[10:11], v[12:13] op_sel_hi:[0,1,1]
	v_pk_fma_f32 v[10:11], v[164:165], s[12:13], v[10:11] op_sel_hi:[0,1,1]
	v_readlane_b32 s6, v26, 62
	v_readlane_b32 s7, v27, 62
	v_readlane_b32 s8, v28, 62
	v_readlane_b32 s9, v29, 62
	v_readlane_b32 s10, v30, 62
	v_readlane_b32 s11, v31, 62
	v_readlane_b32 s12, v32, 62
	v_readlane_b32 s13, v33, 62
	s_waitcnt vmcnt(2)
	v_pk_fma_f32 v[16:17], v[166:167], s[22:23], v[16:17] op_sel_hi:[0,1,1]
	v_pk_fma_f32 v[14:15], v[166:167], s[24:25], v[14:15] op_sel_hi:[0,1,1]
	v_pk_fma_f32 v[12:13], v[166:167], s[26:27], v[12:13] op_sel_hi:[0,1,1]
	v_pk_fma_f32 v[10:11], v[166:167], s[30:31], v[10:11] op_sel_hi:[0,1,1]
	v_readlane_b32 s22, v26, 63
	v_readlane_b32 s23, v27, 63
	v_readlane_b32 s24, v28, 63
	v_readlane_b32 s25, v29, 63
	v_readlane_b32 s26, v30, 63
	v_readlane_b32 s27, v31, 63
	v_readlane_b32 s30, v32, 63
	v_readlane_b32 s31, v33, 63
	s_waitcnt vmcnt(1)
	v_pk_fma_f32 v[16:17], v[168:169], s[6:7], v[16:17] op_sel_hi:[0,1,1]
	v_pk_fma_f32 v[14:15], v[168:169], s[8:9], v[14:15] op_sel_hi:[0,1,1]
	v_pk_fma_f32 v[12:13], v[168:169], s[10:11], v[12:13] op_sel_hi:[0,1,1]
	v_pk_fma_f32 v[10:11], v[168:169], s[12:13], v[10:11] op_sel_hi:[0,1,1]
	s_waitcnt vmcnt(0)
	v_pk_fma_f32 v[16:17], v[170:171], s[22:23], v[16:17] op_sel_hi:[0,1,1]
	v_pk_fma_f32 v[14:15], v[170:171], s[24:25], v[14:15] op_sel_hi:[0,1,1]
	v_pk_fma_f32 v[12:13], v[170:171], s[26:27], v[12:13] op_sel_hi:[0,1,1]
	v_pk_fma_f32 v[10:11], v[170:171], s[30:31], v[10:11] op_sel_hi:[0,1,1]
	s_lshl_b32 s0, s2, 6
	s_and_b32 s0, s0, 0x7c0
	v_or_b32_e32 v3, s0, v2
	v_readlane_b32 s0, v251, 24
	v_lshlrev_b32_e32 v4, 2, v3
	v_mov_b32_e32 v5, v1
	v_readlane_b32 s1, v251, 25
	s_lshl_b32 s90, s4, 13
	s_nop 0
	v_lshl_add_u64 v[4:5], s[0:1], 0, v[4:5]
	v_lshl_add_u64 v[4:5], v[4:5], 0, s[90:91]
	v_add_co_u32_e32 v6, vcc, 0x2000, v4
	global_atomic_add_f32 v[4:5], v16, off
	s_nop 0
	v_addc_co_u32_e32 v7, vcc, 0, v5, vcc
	global_atomic_add_f32 v[6:7], v17, off
	v_add_co_u32_e32 v6, vcc, 0x4000, v4
	v_readlane_b32 s0, v254, 6
	s_nop 0
	v_addc_co_u32_e32 v7, vcc, 0, v5, vcc
	global_atomic_add_f32 v[6:7], v14, off
	v_add_co_u32_e32 v6, vcc, 0x6000, v4
	v_readlane_b32 s1, v254, 7
	s_nop 0
	v_addc_co_u32_e32 v7, vcc, 0, v5, vcc
	global_atomic_add_f32 v[6:7], v15, off
	v_add_co_u32_e32 v6, vcc, 0x8000, v4
	s_add_i32 s2, s2, s0
	s_nop 0
	v_addc_co_u32_e32 v7, vcc, 0, v5, vcc
	global_atomic_add_f32 v[6:7], v12, off
	v_add_co_u32_e32 v6, vcc, 0xa000, v4
	v_readlane_b32 s0, v254, 2
	s_nop 0
	v_addc_co_u32_e32 v7, vcc, 0, v5, vcc
	global_atomic_add_f32 v[6:7], v13, off
	v_add_co_u32_e32 v6, vcc, 0xc000, v4
	s_add_i32 s3, s3, s0
	s_nop 0
	v_addc_co_u32_e32 v7, vcc, 0, v5, vcc
	v_add_co_u32_e32 v4, vcc, 0xe000, v4
	global_atomic_add_f32 v[6:7], v10, off
	s_nop 0
	v_addc_co_u32_e32 v5, vcc, 0, v5, vcc
	global_atomic_add_f32 v[4:5], v11, off
	s_cmpk_gt_i32 s2, 0xfff
	v_readlane_b32 s1, v254, 3
	s_cbranch_scc0 .LBB0_830
